# prep phase de-serialised: all row loads + first weight block issued up front, next weight block staged before the step stores, V^T copy/key-norm/forget-gate loads batched in one burst
# speedup vs baseline: 1.0117x; 1.0117x over previous
; #define LAS __attribute__((address_space(3)))
; DI float bf2f(unsigned short u) { return __uint_as_float((unsigned)u << 16); }
; DI void prep_unit(AP a, int l, int unit, LAS unsigned char* lds, int tid, int lane, int wave) {
;     ...
;     {
;         constexpr int WSZ = 32 * 528;
;         LAS unsigned char* wb = lds + 1024 + half * 2 * WSZ;
;         const int ht = tid & 255;
;         v8s bq[16], bk[8]; float ssq_ = 0.f, ssk_ = 0.f;
; #pragma unroll
;         for (int ks = 0; ks < 16; ++ks) {
;             bq[ks] = *(const v8s*)(proj + (size_t)row * NPROJ + C_CQ + 16 * ks + 8 * hi);
; #pragma unroll
;             for (int jx = 0; jx < 8; ++jx) { const float f = bf2f((unsigned short)bq[ks][jx]); ssq_ += f * f; }
;         }
; #pragma unroll
;         for (int ks = 0; ks < 8; ++ks) {
;             bk[ks] = *(const v8s*)(proj + (size_t)row * NPROJ + C_CKV + 16 * ks + 8 * hi);
; #pragma unroll
;             for (int jx = 0; jx < 8; ++jx) { const float f = bf2f((unsigned short)bk[ks][jx]); ssk_ += f * f; }
;         }
;         ssq_ += __shfl_xor(ssq_, 32); ssk_ += __shfl_xor(ssk_, 32);
;         const float rstdq = rsqrtf(ssq_ * (1.0f / 256.0f) + EPS), rstdk = rsqrtf(ssk_ * (1.0f / 128.0f) + EPS);
;     ...
;         __syncthreads();
;         PW_LOAD(0); PW_STORE(0, 0);
.LBB0_651:
	s_lshl_b32 s2, s14, 7
	v_or_b32_e32 v0, s2, v183
	v_ashrrev_i32_e32 v1, 31, v0
	v_lshlrev_b64 v[2:3], 12, v[0:1]
	v_lshl_add_u64 v[2:3], v[188:189], 0, v[2:3]
	global_load_dwordx4 v[16:19], v[2:3], off offset:3072
	global_load_dwordx4 v[20:23], v[2:3], off offset:3104
	global_load_dwordx4 v[24:27], v[2:3], off offset:3136
	global_load_dwordx4 v[28:31], v[2:3], off offset:3168
	global_load_dwordx4 v[32:35], v[2:3], off offset:3200
	global_load_dwordx4 v[36:39], v[2:3], off offset:3232
	global_load_dwordx4 v[40:43], v[2:3], off offset:3264
	global_load_dwordx4 v[44:47], v[2:3], off offset:3296
	global_load_dwordx4 v[48:51], v[2:3], off offset:3328
	global_load_dwordx4 v[52:55], v[2:3], off offset:3360
	global_load_dwordx4 v[56:59], v[2:3], off offset:3392
	global_load_dwordx4 v[60:63], v[2:3], off offset:3424
	global_load_dwordx4 v[82:85], v[2:3], off offset:3584
	global_load_dwordx4 v[86:89], v[2:3], off offset:3616
	global_load_dwordx4 v[66:69], v[2:3], off offset:3456
	global_load_dwordx4 v[70:73], v[2:3], off offset:3488
	global_load_dwordx4 v[74:77], v[2:3], off offset:3520
	global_load_dwordx4 v[78:81], v[2:3], off offset:3552
	global_load_dwordx4 v[90:93], v[2:3], off offset:3648
	global_load_dwordx4 v[98:101], v[2:3], off offset:3712
	global_load_dwordx4 v[94:97], v[2:3], off offset:3680
	global_load_dwordx4 v[102:105], v[2:3], off offset:3744
	global_load_dwordx4 v[106:109], v[2:3], off offset:3776
	global_load_dwordx4 v[110:113], v[2:3], off offset:3808
	global_load_dwordx4 v[114:117], v[166:167], off
	global_load_dwordx4 v[126:129], v[168:169], off
	global_load_dwordx4 v[118:121], v[176:177], off
	global_load_dwordx4 v[122:125], v[178:179], off
	v_mad_i64_i32 v[204:205], s[6:7], v171, s86, v[196:197]
	s_bfe_i32 s7, s14, 0x10018
	s_lshr_b32 s7, s7, 20
	s_add_i32 s7, s2, s7
	s_and_b32 s7, s7, 0xfffff000
	s_sub_i32 s16, s2, s7
	s_mov_b32 s7, 0x800000
	s_ashr_i32 s15, s14, 31
	s_lshr_b32 s6, s15, 27
	s_add_i32 s6, s14, s6
	s_ashr_i32 s6, s6, 5
	s_mov_b32 s17, 0
	v_mov_b64_e32 v[216:217], v[198:199]
	s_mov_b32 s22, 0
	s_mov_b32 s25, 0x10000
	s_mov_b32 s26, 0x16000
	s_mov_b32 s27, 0x20000
	s_mov_b32 s28, 0x30000
	s_waitcnt vmcnt(27)
	v_and_b32_e32 v1, 0xffff0000, v16
	v_lshlrev_b32_e32 v4, 16, v16
	v_mul_f32_e32 v1, v1, v1
	v_fmac_f32_e32 v1, v4, v4
	v_lshlrev_b32_e32 v4, 16, v17
	v_fmac_f32_e32 v1, v4, v4
	v_and_b32_e32 v4, 0xffff0000, v17
	v_fmac_f32_e32 v1, v4, v4
	v_lshlrev_b32_e32 v4, 16, v18
	v_fmac_f32_e32 v1, v4, v4
	v_and_b32_e32 v4, 0xffff0000, v18
	v_fmac_f32_e32 v1, v4, v4
	v_lshlrev_b32_e32 v4, 16, v19
	v_fmac_f32_e32 v1, v4, v4
	v_and_b32_e32 v4, 0xffff0000, v19
	v_fmac_f32_e32 v1, v4, v4
	s_waitcnt vmcnt(26)
	v_lshlrev_b32_e32 v4, 16, v20
	v_fmac_f32_e32 v1, v4, v4
	v_and_b32_e32 v4, 0xffff0000, v20
	v_fmac_f32_e32 v1, v4, v4
	v_lshlrev_b32_e32 v4, 16, v21
	v_fmac_f32_e32 v1, v4, v4
	v_and_b32_e32 v4, 0xffff0000, v21
	v_fmac_f32_e32 v1, v4, v4
	v_lshlrev_b32_e32 v4, 16, v22
	v_fmac_f32_e32 v1, v4, v4
	v_and_b32_e32 v4, 0xffff0000, v22
	v_fmac_f32_e32 v1, v4, v4
	v_lshlrev_b32_e32 v4, 16, v23
	v_fmac_f32_e32 v1, v4, v4
	v_and_b32_e32 v4, 0xffff0000, v23
	v_fmac_f32_e32 v1, v4, v4
	s_waitcnt vmcnt(25)
	v_lshlrev_b32_e32 v4, 16, v24
	v_fmac_f32_e32 v1, v4, v4
	v_and_b32_e32 v4, 0xffff0000, v24
	v_fmac_f32_e32 v1, v4, v4
	v_lshlrev_b32_e32 v4, 16, v25
	v_fmac_f32_e32 v1, v4, v4
	v_and_b32_e32 v4, 0xffff0000, v25
	v_fmac_f32_e32 v1, v4, v4
	v_lshlrev_b32_e32 v4, 16, v26
	v_fmac_f32_e32 v1, v4, v4
	v_and_b32_e32 v4, 0xffff0000, v26
	v_fmac_f32_e32 v1, v4, v4
	v_lshlrev_b32_e32 v4, 16, v27
	v_fmac_f32_e32 v1, v4, v4
	v_and_b32_e32 v4, 0xffff0000, v27
	v_fmac_f32_e32 v1, v4, v4
	s_waitcnt vmcnt(24)
	v_lshlrev_b32_e32 v4, 16, v28
	v_fmac_f32_e32 v1, v4, v4
	v_and_b32_e32 v4, 0xffff0000, v28
	v_fmac_f32_e32 v1, v4, v4
	v_lshlrev_b32_e32 v4, 16, v29
	v_fmac_f32_e32 v1, v4, v4
	v_and_b32_e32 v4, 0xffff0000, v29
	v_fmac_f32_e32 v1, v4, v4
	v_lshlrev_b32_e32 v4, 16, v30
	v_fmac_f32_e32 v1, v4, v4
	v_and_b32_e32 v4, 0xffff0000, v30
	v_fmac_f32_e32 v1, v4, v4
	v_lshlrev_b32_e32 v4, 16, v31
	v_fmac_f32_e32 v1, v4, v4
	v_and_b32_e32 v4, 0xffff0000, v31
	v_fmac_f32_e32 v1, v4, v4
	s_waitcnt vmcnt(23)
	v_lshlrev_b32_e32 v4, 16, v32
	v_fmac_f32_e32 v1, v4, v4
	v_and_b32_e32 v4, 0xffff0000, v32
	v_fmac_f32_e32 v1, v4, v4
	v_lshlrev_b32_e32 v4, 16, v33
	v_fmac_f32_e32 v1, v4, v4
	v_and_b32_e32 v4, 0xffff0000, v33
	v_fmac_f32_e32 v1, v4, v4
	v_lshlrev_b32_e32 v4, 16, v34
	v_fmac_f32_e32 v1, v4, v4
	v_and_b32_e32 v4, 0xffff0000, v34
	v_fmac_f32_e32 v1, v4, v4
	v_lshlrev_b32_e32 v4, 16, v35
	v_fmac_f32_e32 v1, v4, v4
	v_and_b32_e32 v4, 0xffff0000, v35
	v_fmac_f32_e32 v1, v4, v4
	s_waitcnt vmcnt(22)
	v_lshlrev_b32_e32 v4, 16, v36
	v_fmac_f32_e32 v1, v4, v4
	v_and_b32_e32 v4, 0xffff0000, v36
	v_fmac_f32_e32 v1, v4, v4
	v_lshlrev_b32_e32 v4, 16, v37
	v_fmac_f32_e32 v1, v4, v4
	v_and_b32_e32 v4, 0xffff0000, v37
	v_fmac_f32_e32 v1, v4, v4
	v_lshlrev_b32_e32 v4, 16, v38
	v_fmac_f32_e32 v1, v4, v4
	v_and_b32_e32 v4, 0xffff0000, v38
	v_fmac_f32_e32 v1, v4, v4
	v_lshlrev_b32_e32 v4, 16, v39
	v_fmac_f32_e32 v1, v4, v4
	v_and_b32_e32 v4, 0xffff0000, v39
	v_fmac_f32_e32 v1, v4, v4
	s_waitcnt vmcnt(21)
	v_lshlrev_b32_e32 v4, 16, v40
	v_fmac_f32_e32 v1, v4, v4
	v_and_b32_e32 v4, 0xffff0000, v40
	v_fmac_f32_e32 v1, v4, v4
	v_lshlrev_b32_e32 v4, 16, v41
	v_fmac_f32_e32 v1, v4, v4
	v_and_b32_e32 v4, 0xffff0000, v41
	v_fmac_f32_e32 v1, v4, v4
	v_lshlrev_b32_e32 v4, 16, v42
	v_fmac_f32_e32 v1, v4, v4
	v_and_b32_e32 v4, 0xffff0000, v42
	v_lshlrev_b32_e32 v5, 16, v43
	v_pk_mul_f32 v[4:5], v[4:5], v[4:5]
	s_waitcnt vmcnt(19)
; DI float bf2f(unsigned short u) { return __uint_as_float((unsigned)u << 16); }
; DI void prep_unit(AP a, int l, int unit, LAS unsigned char* lds, int tid, int lane, int wave) {
;     ...
; #pragma unroll
;         for (int ks = 0; ks < 16; ++ks) {
;             bq[ks] = *(const v8s*)(proj + (size_t)row * NPROJ + C_CQ + 16 * ks + 8 * hi);
; #pragma unroll
;             for (int jx = 0; jx < 8; ++jx) { const float f = bf2f((unsigned short)bq[ks][jx]); ssq_ += f * f; }
;         }
; #pragma unroll
;         for (int ks = 0; ks < 8; ++ks) {
;             bk[ks] = *(const v8s*)(proj + (size_t)row * NPROJ + C_CKV + 16 * ks + 8 * hi);
; #pragma unroll
;             for (int jx = 0; jx < 8; ++jx) { const float f = bf2f((unsigned short)bk[ks][jx]); ssk_ += f * f; }
;         }
;         ssq_ += __shfl_xor(ssq_, 32); ssk_ += __shfl_xor(ssk_, 32);
	v_and_b32_e32 v137, 0xffff0000, v48
	v_add_f32_e32 v1, v4, v1
	v_add_f32_e32 v1, v5, v1
	v_and_b32_e32 v5, 0xffff0000, v43
	v_lshlrev_b32_e32 v4, 16, v44
	v_pk_mul_f32 v[4:5], v[4:5], v[4:5]
	s_waitcnt vmcnt(15)
	v_lshlrev_b32_e32 v136, 16, v82
	v_add_f32_e32 v1, v5, v1
	v_add_f32_e32 v1, v4, v1
	v_and_b32_e32 v4, 0xffff0000, v44
	v_lshlrev_b32_e32 v5, 16, v45
	v_pk_mul_f32 v[4:5], v[4:5], v[4:5]
	v_lshlrev_b32_e32 v139, 16, v49
	v_add_f32_e32 v1, v4, v1
	v_add_f32_e32 v1, v5, v1
	v_and_b32_e32 v4, 0xffff0000, v45
	v_lshlrev_b32_e32 v5, 16, v46
	v_pk_mul_f32 v[4:5], v[4:5], v[4:5]
	v_lshlrev_b32_e32 v138, 16, v83
	v_add_f32_e32 v1, v4, v1
	v_add_f32_e32 v1, v5, v1
	v_and_b32_e32 v4, 0xffff0000, v46
	v_lshlrev_b32_e32 v5, 16, v47
	v_pk_mul_f32 v[4:5], v[4:5], v[4:5]
	v_and_b32_e32 v133, 0xffff0000, v49
	v_add_f32_e32 v1, v4, v1
	v_add_f32_e32 v1, v5, v1
	v_and_b32_e32 v5, 0xffff0000, v47
	v_lshlrev_b32_e32 v4, 16, v48
	v_pk_mul_f32 v[4:5], v[4:5], v[4:5]
	v_and_b32_e32 v132, 0xffff0000, v83
	v_add_f32_e32 v1, v5, v1
	v_add_f32_e32 v131, v4, v1
	v_and_b32_e32 v1, 0xffff0000, v82
	v_mul_f32_e32 v130, v1, v1
	v_pk_fma_f32 v[130:131], v[136:137], v[136:137], v[130:131]
	v_and_b32_e32 v141, 0xffff0000, v54
	v_pk_fma_f32 v[130:131], v[138:139], v[138:139], v[130:131]
	v_lshlrev_b32_e32 v139, 16, v54
	v_pk_fma_f32 v[130:131], v[132:133], v[132:133], v[130:131]
	v_lshlrev_b32_e32 v133, 16, v50
	v_lshlrev_b32_e32 v132, 16, v84
	v_pk_fma_f32 v[130:131], v[132:133], v[132:133], v[130:131]
	v_and_b32_e32 v133, 0xffff0000, v50
	v_and_b32_e32 v132, 0xffff0000, v84
	v_pk_fma_f32 v[130:131], v[132:133], v[132:133], v[130:131]
	v_lshlrev_b32_e32 v133, 16, v51
	v_lshlrev_b32_e32 v132, 16, v85
	v_pk_fma_f32 v[130:131], v[132:133], v[132:133], v[130:131]
	v_and_b32_e32 v133, 0xffff0000, v51
	v_and_b32_e32 v132, 0xffff0000, v85
	v_pk_fma_f32 v[130:131], v[132:133], v[132:133], v[130:131]
	v_lshlrev_b32_e32 v133, 16, v52
	s_waitcnt vmcnt(14)
	v_lshlrev_b32_e32 v132, 16, v86
	v_pk_fma_f32 v[130:131], v[132:133], v[132:133], v[130:131]
	v_and_b32_e32 v133, 0xffff0000, v52
	v_and_b32_e32 v132, 0xffff0000, v86
	v_pk_fma_f32 v[130:131], v[132:133], v[132:133], v[130:131]
	v_lshlrev_b32_e32 v133, 16, v53
	v_lshlrev_b32_e32 v132, 16, v87
	v_pk_fma_f32 v[130:131], v[132:133], v[132:133], v[130:131]
	v_and_b32_e32 v133, 0xffff0000, v53
	v_and_b32_e32 v132, 0xffff0000, v87
	v_pk_fma_f32 v[136:137], v[132:133], v[132:133], v[130:131]
	v_lshlrev_b32_e32 v138, 16, v88
	v_and_b32_e32 v140, 0xffff0000, v88
	v_pk_fma_f32 v[136:137], v[138:139], v[138:139], v[136:137]
	v_lshlrev_b32_e32 v135, 16, v55
	v_lshlrev_b32_e32 v134, 16, v89
	v_pk_fma_f32 v[136:137], v[140:141], v[140:141], v[136:137]
	v_pk_fma_f32 v[134:135], v[134:135], v[134:135], v[136:137]
	v_and_b32_e32 v137, 0xffff0000, v55
	v_and_b32_e32 v136, 0xffff0000, v89
	v_pk_fma_f32 v[134:135], v[136:137], v[136:137], v[134:135]
	v_lshlrev_b32_e32 v137, 16, v56
	v_and_b32_e32 v149, 0xffff0000, v59
	v_lshlrev_b32_e32 v153, 16, v60
	v_and_b32_e32 v143, 0xffff0000, v60
	s_waitcnt vmcnt(13)
	v_and_b32_e32 v155, 0xffff0000, v67
	v_lshlrev_b32_e32 v147, 16, v68
	s_waitcnt vmcnt(12)
	v_lshlrev_b32_e32 v157, 16, v73
	v_and_b32_e32 v151, 0xffff0000, v73
	s_waitcnt vmcnt(11)
	v_and_b32_e32 v5, 0xffff0000, v77
	v_lshlrev_b32_e32 v4, 16, v77
	v_pk_mul_f32 v[14:15], v[4:5], v[4:5]
	s_waitcnt vmcnt(10)
	v_and_b32_e32 v5, 0xffff0000, v78
	v_lshlrev_b32_e32 v4, 16, v78
	v_pk_mul_f32 v[12:13], v[4:5], v[4:5]
	v_and_b32_e32 v5, 0xffff0000, v79
	v_lshlrev_b32_e32 v4, 16, v79
	v_mov_b32_e32 v161, v12
	v_pk_mul_f32 v[10:11], v[4:5], v[4:5]
	v_and_b32_e32 v5, 0xffff0000, v80
	v_lshlrev_b32_e32 v4, 16, v80
	v_pk_mul_f32 v[8:9], v[4:5], v[4:5]
	v_and_b32_e32 v5, 0xffff0000, v81
	v_lshlrev_b32_e32 v4, 16, v81
	v_pk_mul_f32 v[6:7], v[4:5], v[4:5]
	v_or_b32_e32 v4, s16, v183
	s_waitcnt vmcnt(9)
	v_lshlrev_b32_e32 v136, 16, v90
	v_pk_fma_f32 v[134:135], v[136:137], v[136:137], v[134:135]
	v_and_b32_e32 v137, 0xffff0000, v56
	v_and_b32_e32 v136, 0xffff0000, v90
	v_pk_fma_f32 v[134:135], v[136:137], v[136:137], v[134:135]
	v_lshlrev_b32_e32 v137, 16, v57
	v_lshlrev_b32_e32 v136, 16, v91
	v_pk_fma_f32 v[134:135], v[136:137], v[136:137], v[134:135]
	v_and_b32_e32 v137, 0xffff0000, v57
	v_and_b32_e32 v136, 0xffff0000, v91
	v_pk_fma_f32 v[134:135], v[136:137], v[136:137], v[134:135]
	v_lshlrev_b32_e32 v137, 16, v58
	v_lshlrev_b32_e32 v136, 16, v92
	v_pk_fma_f32 v[134:135], v[136:137], v[136:137], v[134:135]
	v_and_b32_e32 v137, 0xffff0000, v58
	v_and_b32_e32 v136, 0xffff0000, v92
	v_pk_fma_f32 v[134:135], v[136:137], v[136:137], v[134:135]
	v_lshlrev_b32_e32 v137, 16, v59
	v_lshlrev_b32_e32 v136, 16, v93
	v_pk_fma_f32 v[144:145], v[136:137], v[136:137], v[134:135]
	v_and_b32_e32 v148, 0xffff0000, v93
	v_pk_fma_f32 v[144:145], v[148:149], v[148:149], v[144:145]
	s_waitcnt vmcnt(8)
	v_and_b32_e32 v154, 0xffff0000, v99
	v_lshlrev_b32_e32 v146, 16, v100
	s_waitcnt vmcnt(7)
	v_lshlrev_b32_e32 v152, 16, v94
	v_and_b32_e32 v142, 0xffff0000, v94
	v_pk_fma_f32 v[144:145], v[152:153], v[152:153], v[144:145]
	v_lshlrev_b32_e32 v153, 16, v67
	v_pk_fma_f32 v[142:143], v[142:143], v[142:143], v[144:145]
	v_lshlrev_b32_e32 v145, 16, v61
	v_lshlrev_b32_e32 v144, 16, v95
	v_pk_fma_f32 v[142:143], v[144:145], v[144:145], v[142:143]
	v_and_b32_e32 v145, 0xffff0000, v61
	v_and_b32_e32 v144, 0xffff0000, v95
	v_pk_fma_f32 v[142:143], v[144:145], v[144:145], v[142:143]
	v_lshlrev_b32_e32 v145, 16, v62
	v_lshlrev_b32_e32 v144, 16, v96
	v_pk_fma_f32 v[142:143], v[144:145], v[144:145], v[142:143]
	v_and_b32_e32 v145, 0xffff0000, v62
	v_and_b32_e32 v144, 0xffff0000, v96
	v_pk_fma_f32 v[142:143], v[144:145], v[144:145], v[142:143]
	v_lshlrev_b32_e32 v145, 16, v63
	v_lshlrev_b32_e32 v144, 16, v97
	v_pk_fma_f32 v[142:143], v[144:145], v[144:145], v[142:143]
	v_and_b32_e32 v145, 0xffff0000, v63
	v_and_b32_e32 v144, 0xffff0000, v97
	v_pk_fma_f32 v[142:143], v[144:145], v[144:145], v[142:143]
	v_lshlrev_b32_e32 v145, 16, v66
	v_lshlrev_b32_e32 v144, 16, v98
	v_pk_fma_f32 v[142:143], v[144:145], v[144:145], v[142:143]
	v_and_b32_e32 v145, 0xffff0000, v66
	v_and_b32_e32 v144, 0xffff0000, v98
	v_pk_fma_f32 v[148:149], v[144:145], v[144:145], v[142:143]
	v_lshlrev_b32_e32 v152, 16, v99
	v_pk_fma_f32 v[148:149], v[152:153], v[152:153], v[148:149]
	s_waitcnt vmcnt(6)
; DI void prep_unit(AP a, int l, int unit, LAS unsigned char* lds, int tid, int lane, int wave) {
;     ...
;         ssq_ += __shfl_xor(ssq_, 32); ssk_ += __shfl_xor(ssk_, 32);
;         const float rstdq = rsqrtf(ssq_ * (1.0f / 256.0f) + EPS), rstdk = rsqrtf(ssk_ * (1.0f / 128.0f) + EPS);
;         v4u wreg[4];
;     ...
;         __syncthreads();
;         PW_LOAD(0); PW_STORE(0, 0);
;         __syncthreads();
	v_lshlrev_b32_e32 v156, 16, v105
	v_pk_fma_f32 v[148:149], v[154:155], v[154:155], v[148:149]
	v_and_b32_e32 v155, 0xffff0000, v72
	v_pk_fma_f32 v[146:147], v[146:147], v[146:147], v[148:149]
	v_and_b32_e32 v149, 0xffff0000, v68
	v_and_b32_e32 v148, 0xffff0000, v100
	v_pk_fma_f32 v[146:147], v[148:149], v[148:149], v[146:147]
	v_lshlrev_b32_e32 v149, 16, v69
	v_lshlrev_b32_e32 v148, 16, v101
	v_pk_fma_f32 v[146:147], v[148:149], v[148:149], v[146:147]
	v_and_b32_e32 v149, 0xffff0000, v69
	v_and_b32_e32 v148, 0xffff0000, v101
	v_pk_fma_f32 v[146:147], v[148:149], v[148:149], v[146:147]
	v_lshlrev_b32_e32 v149, 16, v70
	v_lshlrev_b32_e32 v148, 16, v102
	v_pk_fma_f32 v[146:147], v[148:149], v[148:149], v[146:147]
	v_and_b32_e32 v149, 0xffff0000, v70
	v_and_b32_e32 v148, 0xffff0000, v102
	v_pk_fma_f32 v[146:147], v[148:149], v[148:149], v[146:147]
	v_lshlrev_b32_e32 v149, 16, v71
	v_lshlrev_b32_e32 v148, 16, v103
	v_pk_fma_f32 v[146:147], v[148:149], v[148:149], v[146:147]
	v_and_b32_e32 v149, 0xffff0000, v71
	v_and_b32_e32 v148, 0xffff0000, v103
	v_pk_fma_f32 v[146:147], v[148:149], v[148:149], v[146:147]
	v_lshlrev_b32_e32 v149, 16, v72
	v_lshlrev_b32_e32 v148, 16, v104
	v_pk_fma_f32 v[152:153], v[148:149], v[148:149], v[146:147]
	v_and_b32_e32 v154, 0xffff0000, v104
	v_pk_fma_f32 v[152:153], v[154:155], v[154:155], v[152:153]
	v_and_b32_e32 v150, 0xffff0000, v105
	v_pk_fma_f32 v[152:153], v[156:157], v[156:157], v[152:153]
	s_waitcnt vmcnt(5)
	v_and_b32_e32 v159, 0xffff0000, v109
	v_pk_fma_f32 v[150:151], v[150:151], v[150:151], v[152:153]
	v_lshlrev_b32_e32 v153, 16, v74
	v_lshlrev_b32_e32 v152, 16, v106
	v_pk_fma_f32 v[150:151], v[152:153], v[152:153], v[150:151]
	v_and_b32_e32 v153, 0xffff0000, v74
	v_and_b32_e32 v152, 0xffff0000, v106
	v_pk_fma_f32 v[150:151], v[152:153], v[152:153], v[150:151]
	v_lshlrev_b32_e32 v153, 16, v75
	v_lshlrev_b32_e32 v152, 16, v107
	v_pk_fma_f32 v[150:151], v[152:153], v[152:153], v[150:151]
	v_and_b32_e32 v153, 0xffff0000, v75
	v_and_b32_e32 v152, 0xffff0000, v107
	v_lshlrev_b32_e32 v158, 16, v109
	v_pk_fma_f32 v[150:151], v[152:153], v[152:153], v[150:151]
	v_lshlrev_b32_e32 v153, 16, v76
	v_lshlrev_b32_e32 v152, 16, v108
	v_pk_mul_f32 v[158:159], v[158:159], v[158:159]
	v_pk_fma_f32 v[150:151], v[152:153], v[152:153], v[150:151]
	v_and_b32_e32 v153, 0xffff0000, v76
	v_and_b32_e32 v152, 0xffff0000, v108
	v_pk_fma_f32 v[150:151], v[152:153], v[152:153], v[150:151]
	v_mov_b32_e32 v152, v158
	v_mov_b32_e32 v153, v14
	v_pk_add_f32 v[150:151], v[152:153], v[150:151]
	v_mov_b32_e32 v14, v159
	v_pk_add_f32 v[14:15], v[14:15], v[150:151]
	s_barrier
	s_waitcnt vmcnt(4)
	v_and_b32_e32 v3, 0xffff0000, v110
	v_lshlrev_b32_e32 v2, 16, v110
	v_pk_mul_f32 v[2:3], v[2:3], v[2:3]
	v_and_b32_e32 v155, 0xffff0000, v111
	v_lshlrev_b32_e32 v154, 16, v111
	v_mov_b32_e32 v160, v2
	v_pk_mul_f32 v[154:155], v[154:155], v[154:155]
	v_pk_add_f32 v[14:15], v[160:161], v[14:15]
	v_mov_b32_e32 v12, v3
	v_and_b32_e32 v157, 0xffff0000, v112
	v_lshlrev_b32_e32 v156, 16, v112
	v_pk_add_f32 v[2:3], v[12:13], v[14:15]
	v_mov_b32_e32 v12, v154
	v_mov_b32_e32 v13, v10
	v_pk_mul_f32 v[156:157], v[156:157], v[156:157]
	v_pk_add_f32 v[2:3], v[12:13], v[2:3]
	v_mov_b32_e32 v10, v155
	v_and_b32_e32 v159, 0xffff0000, v113
	v_lshlrev_b32_e32 v158, 16, v113
	v_pk_add_f32 v[2:3], v[10:11], v[2:3]
	v_mov_b32_e32 v10, v156
	v_mov_b32_e32 v11, v8
	v_pk_mul_f32 v[158:159], v[158:159], v[158:159]
	v_pk_add_f32 v[2:3], v[10:11], v[2:3]
	v_mov_b32_e32 v8, v157
	v_pk_add_f32 v[2:3], v[8:9], v[2:3]
	v_mov_b32_e32 v8, v158
	v_mov_b32_e32 v9, v6
	v_mov_b32_e32 v6, v159
	v_pk_add_f32 v[2:3], v[8:9], v[2:3]
	s_nop 0
	v_pk_add_f32 v[2:3], v[6:7], v[2:3]
	ds_bpermute_b32 v7, v242, v3
	ds_bpermute_b32 v6, v242, v2
	s_waitcnt lgkmcnt(0)
	v_pk_add_f32 v[2:3], v[2:3], v[6:7]
	v_mov_b32_e32 v6, 0x358637bd
	v_pk_fma_f32 v[6:7], v[2:3], s[34:35], v[6:7] op_sel_hi:[1,1,0]
	s_nop 0
	v_cmp_gt_f32_e64 s[54:55], s7, v6
	v_mul_f32_e32 v3, 0x4b800000, v6
	v_mul_f32_e32 v1, 0x4b800000, v7
	v_cmp_gt_f32_e32 vcc, s7, v7
	v_cndmask_b32_e64 v3, v6, v3, s[54:55]
	v_rsq_f32_e32 v3, v3
	v_cndmask_b32_e32 v1, v7, v1, vcc
	v_rsq_f32_e32 v1, v1
	s_lshl_b32 s7, s6, 2
	v_mul_f32_e32 v5, 0x45800000, v3
	v_cndmask_b32_e64 v206, v3, v5, s[54:55]
	v_mul_f32_e32 v2, 0x45800000, v1
	v_add_u32_e32 v3, v165, v243
	v_add_u32_e32 v5, v165, v244
	v_cndmask_b32_e32 v208, v1, v2, vcc
	v_mov_b32_e32 v209, v208
	v_mov_b32_e32 v207, v206
	s_waitcnt vmcnt(3)
	ds_write_b128 v3, v[114:117] offset:1024
	s_waitcnt vmcnt(2)
	ds_write_b128 v5, v[126:129] offset:1024
	s_waitcnt vmcnt(1)
	ds_write_b128 v3, v[118:121] offset:9472
	s_waitcnt vmcnt(0)
	ds_write_b128 v3, v[122:125] offset:13696
	v_ashrrev_i32_e32 v5, 31, v4
	v_mov_b64_e32 v[2:3], s[60:61]
	v_mad_i64_i32 v[212:213], s[18:19], v0, s86, v[2:3]
	v_lshlrev_b64 v[0:1], 7, v[4:5]
	v_lshl_add_u64 v[210:211], v[4:5], 1, s[10:11]
	v_lshl_add_u64 v[214:215], v[190:191], 0, v[0:1]
	s_waitcnt lgkmcnt(0)
	s_barrier
	s_branch .LBB0_653

; #define LAS __attribute__((address_space(3)))
; DI unsigned pk2(float lo, float hi) { f32x2_t v = {lo, hi}; bf16x2_t b = __builtin_convertvector(v, bf16x2_t); return __builtin_bit_cast(unsigned, b); }
; DI int crow(int r, int hi) { return (r & 3) + 8 * (r >> 2) + 4 * hi; }
; #define MFMA32(a, b, c) __builtin_amdgcn_mfma_f32_32x32x16_bf16((a), (b), (c), 0, 0, 0)
; DI void prep_unit(AP a, int l, int unit, LAS unsigned char* lds, int tid, int lane, int wave) {
;     ...
;         for (int st = 0; st < 14; ++st) {
;             if (st + 1 < 14) PW_LOAD(st + 1);
;             const LAS unsigned char* wp = wb + (st & 1) * WSZ + r32 * 528 + 16 * hi;
;             v16f acc = {};
;             if (st < 6) {
;                 const int cb = half * 6 + st;
; #pragma unroll
;                 for (int ks = 0; ks < 16; ++ks) { const v8s af = *(const LAS v8s*)(wp + 32 * ks); acc = MFMA32(af, bq[ks], acc); }
;     ...
;                 const int cbi = st - 6;
; #pragma unroll
;                 for (int ks = 0; ks < 8; ++ks) { const v8s af = *(const LAS v8s*)(wp + 32 * ks); acc = MFMA32(af, bk[ks], acc); }
; #pragma unroll
;                 for (int r = 0; r < 16; ++r) acc[r] *= rstdk;
;                 const int head = cbi >> 1, off = 32 * (cbi & 1);
;                 if (half == 0) {
; #pragma unroll
;                     for (int g = 0; g < 4; ++g) { v2u w; w.x = pk2(acc[4 * g], acc[4 * g + 1]); w.y = pk2(acc[4 * g + 2], acc[4 * g + 3]); *(v2u*)(km + (size_t)row * 384 + 96 * head + off + 8 * g + 4 * hi) = w; }
;                 } else {
; #pragma unroll
;                     for (int r = 0; r < 16; ++r) { const int d = off + crow(r, hi); vtm[((size_t)(b * 4 + head) * 64 + d) * SEQ + pos] = (bf16)(pk2(acc[r], 0.f) & 0xffffu); }
;                 }
;             }
;             if (st + 1 < 14) PW_STORE(st + 1, (st + 1) & 1);
.LBB0_658:
	s_bitcmp1_b32 s22, 0
	s_cselect_b32 s20, 0x4200, 0
	v_add_u32_e32 v201, s20, v245
	ds_read_b128 v[158:161], v201 offset:1024
	ds_read_b128 v[154:157], v201 offset:1056
	ds_read_b128 v[150:153], v201 offset:1088
	ds_read_b128 v[146:149], v201 offset:1120
	ds_read_b128 v[142:145], v201 offset:1152
	ds_read_b128 v[138:141], v201 offset:1184
	ds_read_b128 v[134:137], v201 offset:1216
	ds_read_b128 v[130:133], v201 offset:1248
	s_cmp_gt_u32 s22, 5
	s_mov_b64 s[20:21], -1
	s_cbranch_scc0 .LBB0_665
	s_waitcnt lgkmcnt(7)
	v_mfma_f32_32x32x16_bf16 v[0:15], v[158:161], v[82:85], 0
	s_add_i32 s20, s22, -6
	s_lshr_b32 s24, s20, 1
	s_and_b32 s23, s17, 32
	s_andn2_b64 vcc, exec, s[76:77]
	s_mov_b64 s[20:21], -1
	s_waitcnt lgkmcnt(6)
	v_mfma_f32_32x32x16_bf16 v[0:15], v[154:157], v[86:89], v[0:15]
	s_waitcnt lgkmcnt(5)
	v_mfma_f32_32x32x16_bf16 v[0:15], v[150:153], v[90:93], v[0:15]
	s_waitcnt lgkmcnt(4)
	v_mfma_f32_32x32x16_bf16 v[0:15], v[146:149], v[94:97], v[0:15]
	s_waitcnt lgkmcnt(3)
	v_mfma_f32_32x32x16_bf16 v[0:15], v[142:145], v[98:101], v[0:15]
	s_waitcnt lgkmcnt(2)
	v_mfma_f32_32x32x16_bf16 v[0:15], v[138:141], v[102:105], v[0:15]
	s_waitcnt lgkmcnt(1)
	v_mfma_f32_32x32x16_bf16 v[0:15], v[134:137], v[106:109], v[0:15]
	s_waitcnt lgkmcnt(0)
	v_mfma_f32_32x32x16_bf16 v[0:15], v[130:133], v[110:113], v[0:15]
	s_nop 11
	v_pk_mul_f32 v[222:223], v[206:207], v[0:1]
	v_pk_mul_f32 v[224:225], v[206:207], v[2:3]
	v_pk_mul_f32 v[218:219], v[206:207], v[4:5]
	v_pk_mul_f32 v[220:221], v[206:207], v[6:7]
	v_pk_mul_f32 v[4:5], v[206:207], v[8:9]
	v_pk_mul_f32 v[6:7], v[206:207], v[10:11]
	v_pk_mul_f32 v[0:1], v[206:207], v[12:13]
	v_pk_mul_f32 v[2:3], v[206:207], v[14:15]
	s_cmp_eq_u32 s22, 13
	s_cbranch_scc1 .Lpw_kv_skip
	s_add_i32 s98, s22, 1
	s_bitcmp1_b32 s98, 0
	s_cselect_b32 s98, 0x4200, 0
	s_add_i32 s98, s94, s98
	v_add_u32_e32 v12, s98, v180
	v_add_u32_e32 v13, v12, v181
	v_add_u32_e32 v12, v12, v246
	s_waitcnt vmcnt(1)
	ds_write_b128 v13, v[114:117] offset:1024
	s_waitcnt vmcnt(0)
	ds_write_b128 v12, v[126:129] offset:1024
.Lpw_kv_skip:
	s_cbranch_vccnz .LBB0_661
	s_add_i32 s20, s24, s7
	s_ashr_i32 s21, s20, 31
	v_or_b32_e32 v10, s23, v182
	s_lshl_b64 s[20:21], s[20:21], 19
	v_lshl_add_u64 v[8:9], v[210:211], 0, s[20:21]
	v_lshlrev_b32_e32 v64, 13, v10
	v_lshl_add_u64 v[8:9], v[8:9], 0, v[64:65]
	v_cvt_pk_bf16_f32 v11, v222, s0
	v_add_co_u32_e32 v10, vcc, 0x2000, v8
	global_store_short v[8:9], v11, off
	v_cvt_pk_bf16_f32 v12, v223, s0
	v_addc_co_u32_e32 v11, vcc, 0, v9, vcc
	global_store_short v[10:11], v12, off
	v_add_co_u32_e32 v10, vcc, 0x4000, v8
	v_cvt_pk_bf16_f32 v12, v224, s0
	s_nop 0
	v_addc_co_u32_e32 v11, vcc, 0, v9, vcc
	global_store_short v[10:11], v12, off
	v_add_co_u32_e32 v10, vcc, 0x6000, v8
	v_cvt_pk_bf16_f32 v12, v225, s0
	s_nop 0
	v_addc_co_u32_e32 v11, vcc, 0, v9, vcc
	global_store_short v[10:11], v12, off
	v_add_co_u32_e32 v10, vcc, s25, v8
	v_cvt_pk_bf16_f32 v12, v218, s0
	s_nop 0
	v_addc_co_u32_e32 v11, vcc, 0, v9, vcc
	s_mov_b32 s20, 0x12000
	global_store_short v[10:11], v12, off
	v_add_co_u32_e32 v10, vcc, s20, v8
	v_cvt_pk_bf16_f32 v12, v219, s0
	s_nop 0
	v_addc_co_u32_e32 v11, vcc, 0, v9, vcc
	s_mov_b32 s20, 0x14000
	global_store_short v[10:11], v12, off
	v_add_co_u32_e32 v10, vcc, s20, v8
	v_cvt_pk_bf16_f32 v12, v220, s0
	s_nop 0
	v_addc_co_u32_e32 v11, vcc, 0, v9, vcc
	global_store_short v[10:11], v12, off
	v_add_co_u32_e32 v10, vcc, s26, v8
	v_cvt_pk_bf16_f32 v12, v221, s0
	s_nop 0
	v_addc_co_u32_e32 v11, vcc, 0, v9, vcc
	global_store_short v[10:11], v12, off
	v_add_co_u32_e32 v10, vcc, s27, v8
	v_cvt_pk_bf16_f32 v12, v4, s0
	s_nop 0
	v_addc_co_u32_e32 v11, vcc, 0, v9, vcc
	s_mov_b32 s20, 0x22000
	global_store_short v[10:11], v12, off
	v_add_co_u32_e32 v10, vcc, s20, v8
	v_cvt_pk_bf16_f32 v12, v5, s0
	s_nop 0
	v_addc_co_u32_e32 v11, vcc, 0, v9, vcc
	s_mov_b32 s20, 0x24000
	global_store_short v[10:11], v12, off
	v_add_co_u32_e32 v10, vcc, s20, v8
	v_cvt_pk_bf16_f32 v12, v6, s0
	s_nop 0
	v_addc_co_u32_e32 v11, vcc, 0, v9, vcc
	s_mov_b32 s20, 0x26000
	global_store_short v[10:11], v12, off
	v_add_co_u32_e32 v10, vcc, s20, v8
	v_cvt_pk_bf16_f32 v12, v7, s0
	s_nop 0
	v_addc_co_u32_e32 v11, vcc, 0, v9, vcc
	global_store_short v[10:11], v12, off
	v_add_co_u32_e32 v10, vcc, s28, v8
	v_cvt_pk_bf16_f32 v12, v0, s0
	s_nop 0
	v_addc_co_u32_e32 v11, vcc, 0, v9, vcc
	s_mov_b32 s20, 0x32000
	global_store_short v[10:11], v12, off
	v_add_co_u32_e32 v10, vcc, s20, v8
	v_cvt_pk_bf16_f32 v12, v1, s0
	s_nop 0
	v_addc_co_u32_e32 v11, vcc, 0, v9, vcc
	global_store_short v[10:11], v12, off
	v_add_co_u32_e32 v10, vcc, 0x34000, v8
	v_cvt_pk_bf16_f32 v12, v2, s0
	s_nop 0
	v_addc_co_u32_e32 v11, vcc, 0, v9, vcc
	v_add_co_u32_e32 v8, vcc, 0x36000, v8
	global_store_short v[10:11], v12, off
	v_cvt_pk_bf16_f32 v10, v3, s0
	v_addc_co_u32_e32 v9, vcc, 0, v9, vcc
	s_mov_b64 s[20:21], 0
	global_store_short v[8:9], v10, off

; DI void prep_unit(AP a, int l, int unit, LAS unsigned char* lds, int tid, int lane, int wave) {
;     ...
;         for (int st = 0; st < 14; ++st) {
;             if (st + 1 < 14) PW_LOAD(st + 1);
;             const LAS unsigned char* wp = wb + (st & 1) * WSZ + r32 * 528 + 16 * hi;
;             v16f acc = {};
;             if (st < 6) {
;                 const int cb = half * 6 + st;
; #pragma unroll
;                 for (int ks = 0; ks < 16; ++ks) { const v8s af = *(const LAS v8s*)(wp + 32 * ks); acc = MFMA32(af, bq[ks], acc); }
; #pragma unroll
;                 for (int r = 0; r < 16; ++r) acc[r] *= rstdq;
;                 if (st % 3 == 2) {
;                     const v4f c0 = *(const v4f*)(rope + (size_t)pos * 32 + 4 * hi), c1 = *(const v4f*)(rope + (size_t)pos * 32 + 8 + 4 * hi);
;                     const v4f s0v = *(const v4f*)(rope + (size_t)pos * 32 + 16 + 4 * hi), s1v = *(const v4f*)(rope + (size_t)pos * 32 + 24 + 4 * hi);
; #pragma unroll
;                     for (int r = 0; r < 8; ++r) {
;                         const float c = (r < 4) ? c0[r & 3] : c1[r & 3], s = (r < 4) ? s0v[r & 3] : s1v[r & 3];
;                         const float x1 = acc[r], x2 = acc[r + 8];
;                         acc[r] = x1 * c - x2 * s; acc[r + 8] = x1 * s + x2 * c;
;                     }
;                 }
; #pragma unroll
;                 for (int g = 0; g < 4; ++g) { v2u w; w.x = pk2(acc[4 * g], acc[4 * g + 1]); w.y = pk2(acc[4 * g + 2], acc[4 * g + 3]); *(v2u*)(qm + (size_t)row * 384 + 32 * cb + 8 * g + 4 * hi) = w; }
;             } else {
;                 const int cbi = st - 6;
; #pragma unroll
;                 for (int ks = 0; ks < 8; ++ks) { const v8s af = *(const LAS v8s*)(wp + 32 * ks); acc = MFMA32(af, bk[ks], acc); }
; #pragma unroll
;                 for (int r = 0; r < 16; ++r) acc[r] *= rstdk;
;                 const int head = cbi >> 1, off = 32 * (cbi & 1);
;                 if (half == 0) {
; #pragma unroll
;                     for (int g = 0; g < 4; ++g) { v2u w; w.x = pk2(acc[4 * g], acc[4 * g + 1]); w.y = pk2(acc[4 * g + 2], acc[4 * g + 3]); *(v2u*)(km + (size_t)row * 384 + 96 * head + off + 8 * g + 4 * hi) = w; }
;                 } else {
; #pragma unroll
;                     for (int r = 0; r < 16; ++r) { const int d = off + crow(r, hi); vtm[((size_t)(b * 4 + head) * 64 + d) * SEQ + pos] = (bf16)(pk2(acc[r], 0.f) & 0xffffu); }
.LBB0_664:
	s_add_i32 s20, s22, 1
	s_branch .LBB0_652

; #define LAS __attribute__((address_space(3)))
; DI unsigned pk2(float lo, float hi) { f32x2_t v = {lo, hi}; bf16x2_t b = __builtin_convertvector(v, bf16x2_t); return __builtin_bit_cast(unsigned, b); }
; #define MFMA32(a, b, c) __builtin_amdgcn_mfma_f32_32x32x16_bf16((a), (b), (c), 0, 0, 0)
; DI void prep_unit(AP a, int l, int unit, LAS unsigned char* lds, int tid, int lane, int wave) {
;     ...
;             if (st < 6) {
;                 const int cb = half * 6 + st;
; #pragma unroll
;                 for (int ks = 0; ks < 16; ++ks) { const v8s af = *(const LAS v8s*)(wp + 32 * ks); acc = MFMA32(af, bq[ks], acc); }
; #pragma unroll
;                 for (int r = 0; r < 16; ++r) acc[r] *= rstdq;
;                 if (st % 3 == 2) {
;                     const v4f c0 = *(const v4f*)(rope + (size_t)pos * 32 + 4 * hi), c1 = *(const v4f*)(rope + (size_t)pos * 32 + 8 + 4 * hi);
;                     const v4f s0v = *(const v4f*)(rope + (size_t)pos * 32 + 16 + 4 * hi), s1v = *(const v4f*)(rope + (size_t)pos * 32 + 24 + 4 * hi);
; #pragma unroll
;                     for (int r = 0; r < 8; ++r) {
;                         const float c = (r < 4) ? c0[r & 3] : c1[r & 3], s = (r < 4) ? s0v[r & 3] : s1v[r & 3];
;                         const float x1 = acc[r], x2 = acc[r + 8];
;                         acc[r] = x1 * c - x2 * s; acc[r + 8] = x1 * s + x2 * c;
;                     }
;                 }
; #pragma unroll
;                 for (int g = 0; g < 4; ++g) { v2u w; w.x = pk2(acc[4 * g], acc[4 * g + 1]); w.y = pk2(acc[4 * g + 2], acc[4 * g + 3]); *(v2u*)(qm + (size_t)row * 384 + 32 * cb + 8 * g + 4 * hi) = w; }
;     ...
;             if (st + 1 < 14) PW_STORE(st + 1, (st + 1) & 1);
.LBB0_666:
	s_waitcnt lgkmcnt(7)
	v_mfma_f32_32x32x16_bf16 v[0:15], v[158:161], v[16:19], 0
	v_mov_b32_e32 v64, s22
	s_waitcnt lgkmcnt(6)
	v_mfma_f32_32x32x16_bf16 v[0:15], v[154:157], v[20:23], v[0:15]
	s_waitcnt lgkmcnt(5)
	v_mfma_f32_32x32x16_bf16 v[0:15], v[150:153], v[24:27], v[0:15]
	s_waitcnt lgkmcnt(4)
	v_mfma_f32_32x32x16_bf16 v[0:15], v[146:149], v[28:31], v[0:15]
	s_waitcnt lgkmcnt(3)
	v_mfma_f32_32x32x16_bf16 v[0:15], v[142:145], v[32:35], v[0:15]
	s_waitcnt lgkmcnt(2)
	v_mfma_f32_32x32x16_bf16 v[0:15], v[138:141], v[36:39], v[0:15]
	s_waitcnt lgkmcnt(1)
	v_mfma_f32_32x32x16_bf16 v[0:15], v[134:137], v[40:43], v[0:15]
	s_waitcnt lgkmcnt(0)
	v_mfma_f32_32x32x16_bf16 v[0:15], v[130:133], v[44:47], v[0:15]
	ds_read_b128 v[130:133], v201 offset:1280
	ds_read_b128 v[134:137], v201 offset:1312
	s_waitcnt lgkmcnt(1)
	v_mfma_f32_32x32x16_bf16 v[0:15], v[130:133], v[48:51], v[0:15]
	s_waitcnt lgkmcnt(0)
	v_mfma_f32_32x32x16_bf16 v[0:15], v[134:137], v[52:55], v[0:15]
	ds_read_b128 v[130:133], v201 offset:1344
	ds_read_b128 v[134:137], v201 offset:1376
	s_waitcnt lgkmcnt(1)
	v_mfma_f32_32x32x16_bf16 v[0:15], v[130:133], v[56:59], v[0:15]
	s_waitcnt lgkmcnt(0)
	v_mfma_f32_32x32x16_bf16 v[0:15], v[134:137], v[60:63], v[0:15]
	ds_read_b128 v[130:133], v201 offset:1408
	ds_read_b128 v[134:137], v201 offset:1440
	s_waitcnt lgkmcnt(1)
	v_mfma_f32_32x32x16_bf16 v[0:15], v[130:133], v[66:69], v[0:15]
	s_waitcnt lgkmcnt(0)
	v_mfma_f32_32x32x16_bf16 v[0:15], v[134:137], v[70:73], v[0:15]
	ds_read_b128 v[130:133], v201 offset:1472
	ds_read_b128 v[134:137], v201 offset:1504
	s_waitcnt lgkmcnt(1)
	v_mfma_f32_32x32x16_bf16 v[0:15], v[130:133], v[74:77], v[0:15]
	v_sub_co_u32_e64 v130, vcc, s22, 3
	s_nop 1
	v_cndmask_b32_e32 v64, v130, v64, vcc
	v_cmp_ne_u32_e32 vcc, 2, v64
	s_and_b64 vcc, exec, vcc
	s_waitcnt lgkmcnt(0)
	v_mfma_f32_32x32x16_bf16 v[0:15], v[134:137], v[78:81], v[0:15]
	s_nop 11
	v_mul_f32_e32 v130, v208, v6
	v_mov_b32_e32 v6, v15
	v_pk_mul_f32 v[136:137], v[208:209], v[0:1]
	v_pk_mul_f32 v[8:9], v[208:209], v[8:9]
	v_pk_mul_f32 v[134:135], v[208:209], v[2:3]
	v_pk_mul_f32 v[2:3], v[208:209], v[10:11]
	v_pk_mul_f32 v[132:133], v[208:209], v[4:5]
	v_pk_mul_f32 v[0:1], v[208:209], v[12:13]
	v_mul_f32_e32 v10, v208, v14
	v_pk_mul_f32 v[4:5], v[208:209], v[6:7]
	s_add_i32 s98, s22, 1
	s_bitcmp1_b32 s98, 0
	s_cselect_b32 s98, 0x4200, 0
	s_add_i32 s98, s94, s98
	s_cmp_lt_u32 s22, 5
	s_cbranch_scc1 .Lpw_q4
	v_add_u32_e32 v12, s98, v180
	v_add_u32_e32 v13, v12, v181
	v_add_u32_e32 v12, v12, v246
	s_waitcnt vmcnt(1)
	ds_write_b128 v13, v[114:117] offset:1024
	s_waitcnt vmcnt(0)
	ds_write_b128 v12, v[126:129] offset:1024
	s_branch .Lpw_q_done
.Lpw_q4:
	v_add_u32_e32 v12, s98, v164
	v_add_u32_e32 v13, v12, v243
	v_add_u32_e32 v12, v12, v244
	s_waitcnt vmcnt(3)
	ds_write_b128 v13, v[114:117] offset:1024
	s_waitcnt vmcnt(2)
	ds_write_b128 v12, v[126:129] offset:1024
	s_waitcnt vmcnt(1)
	ds_write_b128 v13, v[118:121] offset:9472
	s_waitcnt vmcnt(0)
	ds_write_b128 v13, v[122:125] offset:13696
.Lpw_q_done:
	s_cbranch_vccnz .LBB0_668
	global_load_dwordx4 v[12:15], v[214:215], off
	global_load_dwordx4 v[138:141], v[214:215], off offset:32
	global_load_dwordx4 v[142:145], v[214:215], off offset:64
	global_load_dwordx4 v[146:149], v[214:215], off offset:96
	v_mov_b32_e32 v11, v4
	v_mov_b32_e32 v131, v5
	s_waitcnt vmcnt(1)
	v_pk_mul_f32 v[6:7], v[8:9], v[142:143]
	s_nop 0
	v_pk_fma_f32 v[6:7], v[136:137], v[12:13], v[6:7] neg_lo:[0,0,1] neg_hi:[0,0,1]
	v_pk_mul_f32 v[136:137], v[136:137], v[142:143]
	s_nop 0
	v_pk_fma_f32 v[8:9], v[8:9], v[12:13], v[136:137]
	v_pk_mul_f32 v[12:13], v[2:3], v[144:145]
	v_mov_b32_e32 v136, v6
	v_pk_fma_f32 v[12:13], v[134:135], v[14:15], v[12:13] neg_lo:[0,0,1] neg_hi:[0,0,1]
	v_pk_mul_f32 v[134:135], v[134:135], v[144:145]
	v_mov_b32_e32 v137, v7
	v_pk_fma_f32 v[2:3], v[2:3], v[14:15], v[134:135]
	s_waitcnt vmcnt(0)
	v_pk_mul_f32 v[14:15], v[0:1], v[146:147]
	v_mul_f32_e32 v134, v10, v140
	v_pk_fma_f32 v[14:15], v[132:133], v[138:139], v[14:15] neg_lo:[0,0,1] neg_hi:[0,0,1]
	v_pk_mul_f32 v[132:133], v[132:133], v[146:147]
	v_pk_mul_f32 v[10:11], v[10:11], v[148:149]
	v_pk_fma_f32 v[0:1], v[0:1], v[138:139], v[132:133]
	v_mul_f32_e32 v132, v130, v148
	v_mov_b32_e32 v148, v141
	v_pk_mul_f32 v[4:5], v[4:5], v[148:149]
	v_pk_fma_f32 v[130:131], v[130:131], v[140:141], v[10:11] neg_lo:[0,0,1] neg_hi:[0,0,1]
	v_mov_b32_e32 v135, v4
	v_mov_b32_e32 v133, v5
	v_pk_add_f32 v[10:11], v[134:135], v[132:133]
	v_mov_b32_e32 v134, v12
	v_mov_b32_e32 v135, v13
	v_mov_b32_e32 v132, v14
	v_mov_b32_e32 v133, v15
	v_mov_b32_e32 v5, v131
	v_mov_b32_e32 v4, v11
.LBB0_668:
	v_lshl_add_u64 v[6:7], s[90:91], 0, v[204:205]
	v_cvt_pk_bf16_f32 v12, v136, v137
	v_cvt_pk_bf16_f32 v13, v134, v135
	global_store_dwordx2 v[6:7], v[12:13], off offset:-32
	v_cvt_pk_bf16_f32 v12, v132, v133
	v_cvt_pk_bf16_f32 v13, v130, v5
	v_cvt_pk_bf16_f32 v8, v8, v9
	v_cvt_pk_bf16_f32 v9, v2, v3
	v_cvt_pk_bf16_f32 v0, v0, v1
	v_cvt_pk_bf16_f32 v1, v10, v4
	global_store_dwordx2 v[6:7], v[12:13], off offset:-16
	global_store_dwordx2 v[6:7], v[8:9], off
	global_store_dwordx2 v[6:7], v[0:1], off offset:16
	s_add_i32 s20, s22, 1
	s_branch .LBB0_652
; DI void prep_unit(AP a, int l, int unit, LAS unsigned char* lds, int tid, int lane, int wave) {
;     ...
;         const int rl = tid >> 2, q4 = tid & 3; const int rw = t0 + rl, ps = s0 + rl;
;         const v2u x1 = *(const v2u*)(proj + (size_t)rw * NPROJ + C_KR + 4 * q4), x2 = *(const v2u*)(proj + (size_t)rw * NPROJ + C_KR + 16 + 4 * q4);
;         const v4f c = *(const v4f*)(rope + (size_t)ps * 32 + 4 * q4), s = *(const v4f*)(rope + (size_t)ps * 32 + 16 + 4 * q4);
;         const float a1[4] = {bflo(x1.x), bfhi(x1.x), bflo(x1.y), bfhi(x1.y)}, a2[4] = {bflo(x2.x), bfhi(x2.x), bflo(x2.y), bfhi(x2.y)};
;         float o1[4], o2[4];
; #pragma unroll
;         for (int i = 0; i < 4; ++i) { o1[i] = a1[i] * c[i] - a2[i] * s[i]; o2[i] = a1[i] * s[i] + a2[i] * c[i]; }
;         v2u w1, w2; w1.x = pk2(o1[0], o1[1]); w1.y = pk2(o1[2], o1[3]); w2.x = pk2(o2[0], o2[1]); w2.y = pk2(o2[2], o2[3]);
; #pragma unroll
;         for (int h = 0; h < 4; ++h) { *(v2u*)(km + (size_t)rw * 384 + 96 * h + 64 + 4 * q4) = w1; *(v2u*)(km + (size_t)rw * 384 + 96 * h + 80 + 4 * q4) = w2; }
;     ...
; #pragma unroll 4
;     for (int k = 0; k < 12; ++k) {
;         const int it = tid + 512 * k, c = it % 384, rg = it / 384;
;         const int src = c < 128 ? C_SWAV + c : C_FOXV + (c - 128);
;         unsigned short e[8];
; #pragma unroll
;         for (int j = 0; j < 8; ++j) e[j] = proj[(size_t)(t0 + 8 * rg + j) * NPROJ + src];
;         v4u w; w.x = e[0] | ((unsigned)e[1] << 16); w.y = e[2] | ((unsigned)e[3] << 16); w.z = e[4] | ((unsigned)e[5] << 16); w.w = e[6] | ((unsigned)e[7] << 16);
;         bf16* dst = c < 128 ? vts + ((size_t)(b * 2 + (c >> 6)) * 64 + (c & 63)) * SEQ : vtf + ((size_t)(b * 4 + ((c - 128) >> 6)) * 64 + ((c - 128) & 63)) * SEQ;
;         *(v4u*)(dst + s0 + 8 * rg) = w;
;     }
;     {
;         const int tk = tid >> 2, h = tid & 3;
;         const v4u* kp = (const v4u*)(proj + (size_t)(t0 + tk) * NPROJ + C_FOXK + 64 * h);
;         float ss = 0.f;
; #pragma unroll
;         for (int i = 0; i < 8; ++i) { const v4u w = kp[i]; const unsigned e[4] = {w.x, w.y, w.z, w.w};
; #pragma unroll
;             for (int j = 0; j < 4; ++j) { const float lo = bflo(e[j]), hi2 = bfhi(e[j]); ss += lo * lo + hi2 * hi2; } }
;         float nm = sqrtf(ss);
; #pragma unroll
;         for (int o = 4; o < 64; o <<= 1) nm = fmaxf(nm, __shfl_xor(nm, o));
;         LAS float* red = (LAS float*)lds;
.LBB0_673:
	v_add_u32_e32 v10, s2, v247
	v_ashrrev_i32_e32 v11, 31, v10
	v_add_u32_e32 v2, s16, v247
	v_lshlrev_b64 v[0:1], 12, v[10:11]
	v_lshl_add_u64 v[0:1], s[56:57], 0, v[0:1]
	v_mov_b32_e32 v201, v65
	v_ashrrev_i32_e32 v3, 31, v2
	v_lshl_add_u64 v[4:5], v[0:1], 0, v[200:201]
	v_lshlrev_b64 v[2:3], 7, v[2:3]
	global_load_dwordx2 v[12:13], v[4:5], off offset:3840
	global_load_dwordx2 v[14:15], v[4:5], off offset:3872
	v_lshl_add_u64 v[6:7], v[192:193], 0, v[2:3]
	global_load_dwordx4 v[2:5], v[6:7], off
	s_nop 0
	global_load_dwordx4 v[6:9], v[6:7], off offset:64
	s_mov_b32 s98, 0x2aaaaab
	s_lshl_b32 s100, s2, 12
	s_add_u32 s100, s56, s100
	s_addc_u32 s101, s57, 0
	v_mov_b32_e32 v115, v162
	v_mul_hi_u32 v106, v115, s98
	v_mul_u32_u24_e32 v116, 0x60, v106
	v_sub_u32_e32 v109, v115, v116
	v_lshlrev_b32_e32 v117, 2, v109
	v_cmp_gt_u32_e32 vcc, 0x80, v117
	s_nop 1
	v_cndmask_b32_e64 v112, 0, 1, vcc
	v_lshlrev_b32_e32 v116, 9, v112
	v_sub_u32_e32 v116, 0x480, v116
	v_add_u32_e32 v116, v116, v117
	v_lshlrev_b32_e32 v118, 15, v106
	v_lshl_add_u32 v118, v116, 1, v118
	global_load_dwordx2 v[24:25], v118, s[100:101]
	v_add_u32_e32 v118, 0x1000, v118
	global_load_dwordx2 v[26:27], v118, s[100:101]
	v_add_u32_e32 v118, 0x1000, v118
	global_load_dwordx2 v[28:29], v118, s[100:101]
	v_add_u32_e32 v118, 0x1000, v118
	global_load_dwordx2 v[30:31], v118, s[100:101]
	v_add_u32_e32 v118, 0x1000, v118
	global_load_dwordx2 v[32:33], v118, s[100:101]
	v_add_u32_e32 v118, 0x1000, v118
	global_load_dwordx2 v[34:35], v118, s[100:101]
	v_add_u32_e32 v118, 0x1000, v118
	global_load_dwordx2 v[36:37], v118, s[100:101]
	v_add_u32_e32 v118, 0x1000, v118
	global_load_dwordx2 v[38:39], v118, s[100:101]
	v_add_u32_e32 v115, 0x200, v162
	v_mul_hi_u32 v107, v115, s98
	v_mul_u32_u24_e32 v116, 0x60, v107
	v_sub_u32_e32 v110, v115, v116
	v_lshlrev_b32_e32 v117, 2, v110
	v_cmp_gt_u32_e32 vcc, 0x80, v117
	s_nop 1
	v_cndmask_b32_e64 v113, 0, 1, vcc
	v_lshlrev_b32_e32 v116, 9, v113
	v_sub_u32_e32 v116, 0x480, v116
	v_add_u32_e32 v116, v116, v117
	v_lshlrev_b32_e32 v118, 15, v107
	v_lshl_add_u32 v118, v116, 1, v118
	global_load_dwordx2 v[40:41], v118, s[100:101]
	v_add_u32_e32 v118, 0x1000, v118
	global_load_dwordx2 v[42:43], v118, s[100:101]
	v_add_u32_e32 v118, 0x1000, v118
	global_load_dwordx2 v[44:45], v118, s[100:101]
	v_add_u32_e32 v118, 0x1000, v118
	global_load_dwordx2 v[46:47], v118, s[100:101]
	v_add_u32_e32 v118, 0x1000, v118
	global_load_dwordx2 v[48:49], v118, s[100:101]
	v_add_u32_e32 v118, 0x1000, v118
	global_load_dwordx2 v[50:51], v118, s[100:101]
	v_add_u32_e32 v118, 0x1000, v118
	global_load_dwordx2 v[52:53], v118, s[100:101]
	v_add_u32_e32 v118, 0x1000, v118
	global_load_dwordx2 v[54:55], v118, s[100:101]
	v_add_u32_e32 v115, 0x400, v162
	v_mul_hi_u32 v108, v115, s98
	v_mul_u32_u24_e32 v116, 0x60, v108
	v_sub_u32_e32 v111, v115, v116
	v_lshlrev_b32_e32 v117, 2, v111
	v_cmp_gt_u32_e32 vcc, 0x80, v117
	s_nop 1
	v_cndmask_b32_e64 v114, 0, 1, vcc
	v_lshlrev_b32_e32 v116, 9, v114
	v_sub_u32_e32 v116, 0x480, v116
	v_add_u32_e32 v116, v116, v117
	v_lshlrev_b32_e32 v118, 15, v108
	v_lshl_add_u32 v118, v116, 1, v118
	global_load_dwordx2 v[56:57], v118, s[100:101]
	v_add_u32_e32 v118, 0x1000, v118
	global_load_dwordx2 v[58:59], v118, s[100:101]
	v_add_u32_e32 v118, 0x1000, v118
	global_load_dwordx2 v[60:61], v118, s[100:101]
	v_add_u32_e32 v118, 0x1000, v118
	global_load_dwordx2 v[62:63], v118, s[100:101]
	v_add_u32_e32 v118, 0x1000, v118
	global_load_dwordx2 v[66:67], v118, s[100:101]
	v_add_u32_e32 v118, 0x1000, v118
	global_load_dwordx2 v[68:69], v118, s[100:101]
	v_add_u32_e32 v118, 0x1000, v118
	global_load_dwordx2 v[70:71], v118, s[100:101]
	v_add_u32_e32 v118, 0x1000, v118
	global_load_dwordx2 v[72:73], v118, s[100:101]
	v_or_b32_e32 v119, s2, v163
	v_lshlrev_b32_e32 v119, 12, v119
	global_load_dwordx2 v[124:125], v119, s[56:57] offset:3904
	v_add_u32_e32 v116, 0x1000, v119
	global_load_dwordx2 v[128:129], v116, s[56:57] offset:3904
	s_load_dwordx2 s[100:101], s[64:65], 0x18
	v_readlane_b32 s98, v255, 5
	v_readlane_b32 s99, v255, 6
	s_lshl_b64 s[98:99], s[98:99], 2
	s_waitcnt lgkmcnt(0)
	s_add_u32 s100, s100, s98
	s_addc_u32 s101, s101, s99
	global_load_dwordx4 v[120:123], v65, s[100:101]
	s_mov_b32 s99, 0x7060302
	v_mov_b32_e32 v203, v65
	v_lshl_add_u64 v[126:127], v[0:1], 0, v[202:203]
	global_load_dwordx4 v[130:133], v[126:127], off offset:2048
	global_load_dwordx4 v[134:137], v[126:127], off offset:2064
	global_load_dwordx4 v[138:141], v[126:127], off offset:2080
	global_load_dwordx4 v[142:145], v[126:127], off offset:2096
	global_load_dwordx4 v[146:149], v[126:127], off offset:2112
	global_load_dwordx4 v[150:153], v[126:127], off offset:2128
	global_load_dwordx4 v[154:157], v[126:127], off offset:2144
	global_load_dwordx4 v[158:161], v[126:127], off offset:2160
	s_ashr_i32 s17, s16, 31
	s_lshl_b32 s6, s6, 1
	s_mov_b32 s20, 0
	s_waitcnt vmcnt(38)
	v_lshlrev_b32_e32 v16, 16, v12
	s_waitcnt vmcnt(37)
	v_lshlrev_b32_e32 v18, 16, v14
	v_and_b32_e32 v19, 0xffff0000, v14
	v_and_b32_e32 v17, 0xffff0000, v12
	s_waitcnt vmcnt(35)
	v_pk_mul_f32 v[20:21], v[6:7], v[18:19]
	v_lshlrev_b32_e32 v12, 16, v15
	v_pk_fma_f32 v[20:21], v[2:3], v[16:17], v[20:21] neg_lo:[0,0,1] neg_hi:[0,0,1]
	v_pk_mul_f32 v[2:3], v[2:3], v[18:19]
	s_nop 0
	v_pk_fma_f32 v[2:3], v[6:7], v[16:17], v[2:3]
	v_lshlrev_b32_e32 v6, 16, v13
	v_and_b32_e32 v7, 0xffff0000, v13
	v_and_b32_e32 v13, 0xffff0000, v15
	v_pk_mul_f32 v[14:15], v[8:9], v[12:13]
	v_cvt_pk_bf16_f32 v2, v2, v3
	v_pk_fma_f32 v[14:15], v[4:5], v[6:7], v[14:15] neg_lo:[0,0,1] neg_hi:[0,0,1]
	v_pk_mul_f32 v[4:5], v[4:5], v[12:13]
	s_nop 0
	v_pk_fma_f32 v[4:5], v[8:9], v[6:7], v[4:5]
	v_cvt_pk_bf16_f32 v6, v20, v21
	v_cvt_pk_bf16_f32 v7, v14, v15
	v_cvt_pk_bf16_f32 v3, v4, v5
	v_mad_i64_i32 v[4:5], s[18:19], v10, s86, v[194:195]
	global_store_dwordx2 v[4:5], v[6:7], off offset:128
	global_store_dwordx2 v[4:5], v[2:3], off offset:160
	global_store_dwordx2 v[4:5], v[6:7], off offset:320
	global_store_dwordx2 v[4:5], v[2:3], off offset:352
	global_store_dwordx2 v[4:5], v[6:7], off offset:512
	global_store_dwordx2 v[4:5], v[2:3], off offset:544
	global_store_dwordx2 v[4:5], v[6:7], off offset:704
	global_store_dwordx2 v[4:5], v[2:3], off offset:736
	s_branch .LBB0_675
; DI void prep_unit(AP a, int l, int unit, LAS unsigned char* lds, int tid, int lane, int wave) {
;     ...
; #pragma unroll 4
;     for (int k = 0; k < 12; ++k) {
;         const int it = tid + 512 * k, c = it % 384, rg = it / 384;
;         const int src = c < 128 ? C_SWAV + c : C_FOXV + (c - 128);
;         unsigned short e[8];
; #pragma unroll
;         for (int j = 0; j < 8; ++j) e[j] = proj[(size_t)(t0 + 8 * rg + j) * NPROJ + src];
;         v4u w; w.x = e[0] | ((unsigned)e[1] << 16); w.y = e[2] | ((unsigned)e[3] << 16); w.z = e[4] | ((unsigned)e[5] << 16); w.w = e[6] | ((unsigned)e[7] << 16);
;         bf16* dst = c < 128 ? vts + ((size_t)(b * 2 + (c >> 6)) * 64 + (c & 63)) * SEQ : vtf + ((size_t)(b * 4 + ((c - 128) >> 6)) * 64 + ((c - 128) & 63)) * SEQ;
;         *(v4u*)(dst + s0 + 8 * rg) = w;
;     }
.LBB0_675:
	s_waitcnt vmcnt(35)
	v_perm_b32 v74, v26, v24, s89
	v_perm_b32 v75, v30, v28, s89
	v_perm_b32 v76, v34, v32, s89
	v_perm_b32 v77, v38, v36, s89
	v_perm_b32 v78, v26, v24, s99
	v_perm_b32 v79, v30, v28, s99
	v_perm_b32 v80, v34, v32, s99
	v_perm_b32 v81, v38, v36, s99
	v_perm_b32 v82, v27, v25, s89
	v_perm_b32 v83, v31, v29, s89
	v_perm_b32 v84, v35, v33, s89
	v_perm_b32 v85, v39, v37, s89
	v_perm_b32 v86, v27, v25, s99
	v_perm_b32 v87, v31, v29, s99
	v_perm_b32 v88, v35, v33, s99
	v_perm_b32 v89, v39, v37, s99
	v_lshrrev_b32_e32 v115, 4, v109
	v_add_u32_e32 v117, s7, v115
	v_add_u32_e32 v117, -2, v117
	v_add_u32_e32 v115, s6, v115
	v_cmp_ne_u32_e32 vcc, 0, v112
	s_nop 1
	v_cndmask_b32_e32 v115, v117, v115, vcc
	v_lshlrev_b32_e32 v115, 19, v115
	v_lshlrev_b32_e32 v116, 23, v112
	v_sub_u32_e32 v116, 0x16800000, v116
	v_add_u32_e32 v115, v115, v116
	v_and_b32_e32 v116, 15, v109
	v_lshl_add_u32 v115, v116, 15, v115
	v_lshl_add_u32 v115, v106, 4, v115
	s_lshl_b32 s100, s16, 1
	v_add_u32_e32 v115, s100, v115
	v_add_u32_e32 v116, 0x2000, v115
	v_add_u32_e32 v117, 0x4000, v115
	v_add_u32_e32 v118, 0x6000, v115
	global_store_dwordx4 v115, v[74:77], s[90:91]
	global_store_dwordx4 v116, v[78:81], s[90:91]
	global_store_dwordx4 v117, v[82:85], s[90:91]
	global_store_dwordx4 v118, v[86:89], s[90:91]
	s_waitcnt vmcnt(31)
	v_perm_b32 v90, v42, v40, s89
	v_perm_b32 v91, v46, v44, s89
	v_perm_b32 v92, v50, v48, s89
	v_perm_b32 v93, v54, v52, s89
	v_perm_b32 v94, v42, v40, s99
	v_perm_b32 v95, v46, v44, s99
	v_perm_b32 v96, v50, v48, s99
	v_perm_b32 v97, v54, v52, s99
	v_perm_b32 v98, v43, v41, s89
	v_perm_b32 v99, v47, v45, s89
	v_perm_b32 v100, v51, v49, s89
	v_perm_b32 v101, v55, v53, s89
	v_perm_b32 v102, v43, v41, s99
	v_perm_b32 v103, v47, v45, s99
	v_perm_b32 v104, v51, v49, s99
	v_perm_b32 v105, v55, v53, s99
	v_lshrrev_b32_e32 v115, 4, v110
	v_add_u32_e32 v117, s7, v115
	v_add_u32_e32 v117, -2, v117
	v_add_u32_e32 v115, s6, v115
	v_cmp_ne_u32_e32 vcc, 0, v113
	s_nop 1
	v_cndmask_b32_e32 v115, v117, v115, vcc
	v_lshlrev_b32_e32 v115, 19, v115
	v_lshlrev_b32_e32 v116, 23, v113
	v_sub_u32_e32 v116, 0x16800000, v116
	v_add_u32_e32 v115, v115, v116
	v_and_b32_e32 v116, 15, v110
	v_lshl_add_u32 v115, v116, 15, v115
	v_lshl_add_u32 v115, v107, 4, v115
	s_lshl_b32 s100, s16, 1
	v_add_u32_e32 v115, s100, v115
	v_add_u32_e32 v116, 0x2000, v115
	v_add_u32_e32 v117, 0x4000, v115
	v_add_u32_e32 v118, 0x6000, v115
	global_store_dwordx4 v115, v[90:93], s[90:91]
	global_store_dwordx4 v116, v[94:97], s[90:91]
	global_store_dwordx4 v117, v[98:101], s[90:91]
	global_store_dwordx4 v118, v[102:105], s[90:91]
	s_waitcnt vmcnt(27)
	v_perm_b32 v74, v58, v56, s89
	v_perm_b32 v75, v62, v60, s89
	v_perm_b32 v76, v68, v66, s89
	v_perm_b32 v77, v72, v70, s89
	v_perm_b32 v78, v58, v56, s99
	v_perm_b32 v79, v62, v60, s99
	v_perm_b32 v80, v68, v66, s99
	v_perm_b32 v81, v72, v70, s99
	v_perm_b32 v82, v59, v57, s89
	v_perm_b32 v83, v63, v61, s89
	v_perm_b32 v84, v69, v67, s89
	v_perm_b32 v85, v73, v71, s89
	v_perm_b32 v86, v59, v57, s99
	v_perm_b32 v87, v63, v61, s99
	v_perm_b32 v88, v69, v67, s99
	v_perm_b32 v89, v73, v71, s99
	v_lshrrev_b32_e32 v115, 4, v111
	v_add_u32_e32 v117, s7, v115
	v_add_u32_e32 v117, -2, v117
	v_add_u32_e32 v115, s6, v115
	v_cmp_ne_u32_e32 vcc, 0, v114
	s_nop 1
	v_cndmask_b32_e32 v115, v117, v115, vcc
	v_lshlrev_b32_e32 v115, 19, v115
	v_lshlrev_b32_e32 v116, 23, v114
	v_sub_u32_e32 v116, 0x16800000, v116
	v_add_u32_e32 v115, v115, v116
	v_and_b32_e32 v116, 15, v111
	v_lshl_add_u32 v115, v116, 15, v115
	v_lshl_add_u32 v115, v108, 4, v115
	s_lshl_b32 s100, s16, 1
	v_add_u32_e32 v115, s100, v115
	v_add_u32_e32 v116, 0x2000, v115
	v_add_u32_e32 v117, 0x4000, v115
	v_add_u32_e32 v118, 0x6000, v115
	global_store_dwordx4 v115, v[74:77], s[90:91]
	global_store_dwordx4 v116, v[78:81], s[90:91]
	global_store_dwordx4 v117, v[82:85], s[90:91]
	global_store_dwordx4 v118, v[86:89], s[90:91]
; #define LAS __attribute__((address_space(3)))
; DI float bflo(unsigned u) { return __uint_as_float(u << 16); }
; DI float bfhi(unsigned u) { return __uint_as_float(u & 0xffff0000u); }
; DI void prep_unit(AP a, int l, int unit, LAS unsigned char* lds, int tid, int lane, int wave) {
;     ...
;         const int tk = tid >> 2, h = tid & 3;
;         const v4u* kp = (const v4u*)(proj + (size_t)(t0 + tk) * NPROJ + C_FOXK + 64 * h);
;         float ss = 0.f;
; #pragma unroll
;         for (int i = 0; i < 8; ++i) { const v4u w = kp[i]; const unsigned e[4] = {w.x, w.y, w.z, w.w};
; #pragma unroll
;             for (int j = 0; j < 4; ++j) { const float lo = bflo(e[j]), hi2 = bfhi(e[j]); ss += lo * lo + hi2 * hi2; } }
;         float nm = sqrtf(ss);
; #pragma unroll
;         for (int o = 4; o < 64; o <<= 1) nm = fmaxf(nm, __shfl_xor(nm, o));
;         LAS float* red = (LAS float*)lds;
;         __syncthreads();
;         if (lane < 4) red[wave * 4 + lane] = nm;
;         __syncthreads();
.LBB0_691:
	s_waitcnt vmcnt(20)
	v_mov_b64_e32 v[0:1], v[142:143]
	v_mov_b64_e32 v[2:3], v[144:145]
	v_mov_b64_e32 v[4:5], v[138:139]
	v_mov_b64_e32 v[6:7], v[140:141]
	v_mov_b64_e32 v[8:9], v[134:135]
	v_mov_b64_e32 v[10:11], v[136:137]
	v_mov_b64_e32 v[14:15], v[130:131]
	v_mov_b64_e32 v[16:17], v[132:133]
	v_lshlrev_b32_e32 v18, 16, v14
	v_and_b32_e32 v14, 0xffff0000, v14
	v_mul_f32_e32 v14, v14, v14
	v_fmac_f32_e32 v14, v18, v18
	v_lshlrev_b32_e32 v18, 16, v15
	v_and_b32_e32 v15, 0xffff0000, v15
	v_mul_f32_e32 v15, v15, v15
	v_fmac_f32_e32 v15, v18, v18
	v_add_f32_e32 v14, v14, v15
	v_lshlrev_b32_e32 v15, 16, v16
	v_and_b32_e32 v16, 0xffff0000, v16
	v_mul_f32_e32 v16, v16, v16
	v_fmac_f32_e32 v16, v15, v15
	v_add_f32_e32 v14, v16, v14
	v_and_b32_e32 v16, 0xffff0000, v17
	v_lshlrev_b32_e32 v15, 16, v17
	v_mul_f32_e32 v16, v16, v16
	v_fmac_f32_e32 v16, v15, v15
	v_lshlrev_b32_e32 v15, 16, v8
	v_and_b32_e32 v8, 0xffff0000, v8
	v_mul_f32_e32 v8, v8, v8
	v_add_f32_e32 v14, v16, v14
	v_fmac_f32_e32 v8, v15, v15
	v_add_f32_e32 v8, v8, v14
	v_lshlrev_b32_e32 v14, 16, v9
	v_and_b32_e32 v9, 0xffff0000, v9
	v_mul_f32_e32 v9, v9, v9
	v_fmac_f32_e32 v9, v14, v14
	v_add_f32_e32 v8, v9, v8
	v_lshlrev_b32_e32 v9, 16, v10
	v_and_b32_e32 v10, 0xffff0000, v10
	v_mul_f32_e32 v10, v10, v10
	v_fmac_f32_e32 v10, v9, v9
	v_add_f32_e32 v8, v10, v8
	v_and_b32_e32 v10, 0xffff0000, v11
	v_lshlrev_b32_e32 v9, 16, v11
	v_mul_f32_e32 v10, v10, v10
	v_fmac_f32_e32 v10, v9, v9
	v_lshlrev_b32_e32 v9, 16, v4
	v_and_b32_e32 v4, 0xffff0000, v4
	v_mul_f32_e32 v4, v4, v4
	v_add_f32_e32 v8, v10, v8
	v_fmac_f32_e32 v4, v9, v9
	v_add_f32_e32 v4, v4, v8
	v_lshlrev_b32_e32 v8, 16, v5
	v_and_b32_e32 v5, 0xffff0000, v5
	v_mul_f32_e32 v5, v5, v5
	v_fmac_f32_e32 v5, v8, v8
	v_add_f32_e32 v4, v5, v4
	v_lshlrev_b32_e32 v5, 16, v6
	v_and_b32_e32 v6, 0xffff0000, v6
	v_mul_f32_e32 v6, v6, v6
	v_fmac_f32_e32 v6, v5, v5
	v_add_f32_e32 v4, v6, v4
	v_and_b32_e32 v6, 0xffff0000, v7
	v_lshlrev_b32_e32 v5, 16, v7
	v_mul_f32_e32 v6, v6, v6
	v_fmac_f32_e32 v6, v5, v5
	v_lshlrev_b32_e32 v5, 16, v0
	v_and_b32_e32 v0, 0xffff0000, v0
	v_mul_f32_e32 v0, v0, v0
	v_add_f32_e32 v4, v6, v4
	v_fmac_f32_e32 v0, v5, v5
	v_add_f32_e32 v0, v0, v4
	v_lshlrev_b32_e32 v4, 16, v1
	v_and_b32_e32 v1, 0xffff0000, v1
	v_mul_f32_e32 v1, v1, v1
	v_fmac_f32_e32 v1, v4, v4
	v_add_f32_e32 v0, v1, v0
	v_lshlrev_b32_e32 v1, 16, v2
	v_and_b32_e32 v2, 0xffff0000, v2
	v_mul_f32_e32 v2, v2, v2
	v_fmac_f32_e32 v2, v1, v1
	v_add_f32_e32 v0, v2, v0
	v_and_b32_e32 v2, 0xffff0000, v3
	v_lshlrev_b32_e32 v1, 16, v3
	v_mul_f32_e32 v2, v2, v2
	v_fmac_f32_e32 v2, v1, v1
	v_add_f32_e32 v16, v2, v0
	v_mov_b64_e32 v[0:1], v[158:159]
	v_mov_b64_e32 v[2:3], v[160:161]
	v_mov_b64_e32 v[4:5], v[154:155]
	v_mov_b64_e32 v[6:7], v[156:157]
	v_mov_b64_e32 v[8:9], v[150:151]
	v_mov_b64_e32 v[10:11], v[152:153]
	v_mov_b64_e32 v[12:13], v[146:147]
	v_mov_b64_e32 v[14:15], v[148:149]
	s_barrier
	v_lshlrev_b32_e32 v17, 16, v12
	v_and_b32_e32 v12, 0xffff0000, v12
	v_mul_f32_e32 v12, v12, v12
	v_fmac_f32_e32 v12, v17, v17
	v_add_f32_e32 v12, v12, v16
	v_lshlrev_b32_e32 v16, 16, v13
	v_and_b32_e32 v13, 0xffff0000, v13
	v_mul_f32_e32 v13, v13, v13
	v_fmac_f32_e32 v13, v16, v16
	v_add_f32_e32 v12, v13, v12
	v_lshlrev_b32_e32 v13, 16, v14
	v_and_b32_e32 v14, 0xffff0000, v14
	v_mul_f32_e32 v14, v14, v14
	v_fmac_f32_e32 v14, v13, v13
	v_add_f32_e32 v12, v14, v12
	v_and_b32_e32 v14, 0xffff0000, v15
	v_lshlrev_b32_e32 v13, 16, v15
	v_mul_f32_e32 v14, v14, v14
	v_fmac_f32_e32 v14, v13, v13
	v_lshlrev_b32_e32 v13, 16, v8
	v_and_b32_e32 v8, 0xffff0000, v8
	v_mul_f32_e32 v8, v8, v8
	v_add_f32_e32 v12, v14, v12
	v_fmac_f32_e32 v8, v13, v13
	v_add_f32_e32 v8, v8, v12
	v_lshlrev_b32_e32 v12, 16, v9
	v_and_b32_e32 v9, 0xffff0000, v9
	v_mul_f32_e32 v9, v9, v9
	v_fmac_f32_e32 v9, v12, v12
	v_add_f32_e32 v8, v9, v8
	v_lshlrev_b32_e32 v9, 16, v10
	v_and_b32_e32 v10, 0xffff0000, v10
	v_mul_f32_e32 v10, v10, v10
	v_fmac_f32_e32 v10, v9, v9
	v_add_f32_e32 v8, v10, v8
	v_and_b32_e32 v10, 0xffff0000, v11
	v_lshlrev_b32_e32 v9, 16, v11
	v_mul_f32_e32 v10, v10, v10
	v_fmac_f32_e32 v10, v9, v9
	v_lshlrev_b32_e32 v9, 16, v4
	v_and_b32_e32 v4, 0xffff0000, v4
	v_mul_f32_e32 v4, v4, v4
	v_add_f32_e32 v8, v10, v8
	v_fmac_f32_e32 v4, v9, v9
	v_add_f32_e32 v4, v4, v8
	v_lshlrev_b32_e32 v8, 16, v5
	v_and_b32_e32 v5, 0xffff0000, v5
	v_mul_f32_e32 v5, v5, v5
	v_fmac_f32_e32 v5, v8, v8
	v_add_f32_e32 v4, v5, v4
	v_lshlrev_b32_e32 v5, 16, v6
	v_and_b32_e32 v6, 0xffff0000, v6
	v_mul_f32_e32 v6, v6, v6
	v_fmac_f32_e32 v6, v5, v5
	v_add_f32_e32 v4, v6, v4
	v_and_b32_e32 v6, 0xffff0000, v7
	v_lshlrev_b32_e32 v5, 16, v7
	v_mul_f32_e32 v6, v6, v6
	v_fmac_f32_e32 v6, v5, v5
	v_lshlrev_b32_e32 v5, 16, v0
	v_and_b32_e32 v0, 0xffff0000, v0
	v_mul_f32_e32 v0, v0, v0
	v_add_f32_e32 v4, v6, v4
	v_fmac_f32_e32 v0, v5, v5
	v_add_f32_e32 v0, v0, v4
	v_lshlrev_b32_e32 v4, 16, v1
	v_and_b32_e32 v1, 0xffff0000, v1
	v_mul_f32_e32 v1, v1, v1
	v_fmac_f32_e32 v1, v4, v4
	v_add_f32_e32 v0, v1, v0
	v_lshlrev_b32_e32 v1, 16, v2
	v_and_b32_e32 v2, 0xffff0000, v2
	v_mul_f32_e32 v2, v2, v2
	v_fmac_f32_e32 v2, v1, v1
	v_add_f32_e32 v0, v2, v0
	v_and_b32_e32 v2, 0xffff0000, v3
	v_lshlrev_b32_e32 v1, 16, v3
	v_mul_f32_e32 v2, v2, v2
	v_fmac_f32_e32 v2, v1, v1
	v_add_f32_e32 v0, v2, v0
	v_cmp_gt_f32_e32 vcc, s87, v0
	v_mul_f32_e32 v1, 0x4f800000, v0
	s_nop 0
	v_cndmask_b32_e32 v0, v0, v1, vcc
	v_sqrt_f32_e32 v1, v0
	s_nop 0
	v_add_u32_e32 v2, -1, v1
	v_fma_f32 v3, -v2, v1, v0
	v_cmp_ge_f32_e64 s[54:55], 0, v3
	v_add_u32_e32 v3, 1, v1
	s_nop 0
	v_cndmask_b32_e64 v2, v1, v2, s[54:55]
	v_fma_f32 v1, -v3, v1, v0
	v_cmp_lt_f32_e64 s[54:55], 0, v1
	s_nop 1
	v_cndmask_b32_e64 v1, v2, v3, s[54:55]
	v_mul_f32_e32 v2, 0x37800000, v1
	v_cndmask_b32_e32 v1, v1, v2, vcc
	v_cmp_class_f32_e32 vcc, v0, v229
	s_nop 1
	v_cndmask_b32_e32 v0, v1, v0, vcc
	ds_bpermute_b32 v1, v248, v0
	s_waitcnt lgkmcnt(0)
	v_max_f32_e32 v1, v1, v1
	v_max_f32_e32 v0, v0, v1
	ds_bpermute_b32 v1, v249, v0
	s_waitcnt lgkmcnt(0)
	v_max_f32_e32 v1, v1, v1
	v_max_f32_e32 v0, v0, v1
	ds_bpermute_b32 v1, v250, v0
	s_waitcnt lgkmcnt(0)
	v_max_f32_e32 v1, v1, v1
	v_max_f32_e32 v0, v0, v1
	ds_bpermute_b32 v1, v242, v0
	s_and_saveexec_b64 s[16:17], s[38:39]
	s_cbranch_execz .LBB0_693
	s_waitcnt lgkmcnt(0)
	v_max_f32_e32 v1, v1, v1
	v_max_f32_e32 v0, v0, v0
	v_max_f32_e32 v0, v0, v1
	ds_write_b32 v251, v0

; DI float bflo(unsigned u) { return __uint_as_float(u << 16); }
; DI float bfhi(unsigned u) { return __uint_as_float(u & 0xffff0000u); }
; DI void prep_unit(AP a, int l, int unit, LAS unsigned char* lds, int tid, int lane, int wave) {
;     ...
;     if (wave == 7) {
;         const float* fb = a->in[I_FB] + l * 4;
;         float* floc = (float*)(ws + WS_FLOC); float* ftot = (float*)(ws + WS_FTOT);
;         const int r0 = t0 + 2 * lane;
;         const v2u z0 = *(const v2u*)(proj + (size_t)r0 * NPROJ + C_FL), z1 = *(const v2u*)(proj + (size_t)(r0 + 1) * NPROJ + C_FL);
;         const float za[4] = {bflo(z0.x), bfhi(z0.x), bflo(z0.y), bfhi(z0.y)}, zb[4] = {bflo(z1.x), bfhi(z1.x), bflo(z1.y), bfhi(z1.y)};
;         v4f o0, o1, tt;
; #pragma unroll
;         for (int h = 0; h < 4; ++h) {
;             const float xa = za[h] + fb[h], xb = zb[h] + fb[h];
;             const float la = fminf(xa, 0.f) - __logf(1.0f + __expf(-fabsf(xa))), lb = fminf(xb, 0.f) - __logf(1.0f + __expf(-fabsf(xb)));
;             const float tot = la + lb; float sc = tot;
; #pragma unroll
;             for (int o = 1; o < 64; o <<= 1) { const float v = __shfl_up(sc, o); if (lane >= o) sc += v; }
.LBB0_696:
	v_or_b32_e32 v12, s2, v163
	v_or_b32_e32 v14, 1, v12
	v_ashrrev_i32_e32 v13, 31, v12
	v_ashrrev_i32_e32 v15, 31, v14
	v_lshlrev_b64 v[0:1], 12, v[12:13]
	v_lshlrev_b64 v[2:3], 12, v[14:15]
	v_lshl_add_u64 v[0:1], s[56:57], 0, v[0:1]
	v_lshl_add_u64 v[2:3], s[56:57], 0, v[2:3]
	v_mov_b64_e32 v[0:1], v[124:125]
	v_mov_b64_e32 v[2:3], v[128:129]
	s_mov_b32 s2, 0x800000
	s_mov_b32 s16, 0x7f800000
	v_mov_b32_e32 v20, 0x41b17218
	v_lshl_add_u64 v[12:13], v[12:13], 4, s[12:13]
	v_lshlrev_b32_e32 v4, 16, v0
	v_and_b32_e32 v5, 0xffff0000, v0
	v_lshlrev_b32_e32 v6, 16, v1
	v_and_b32_e32 v7, 0xffff0000, v1
	v_lshlrev_b32_e32 v8, 16, v2
	v_and_b32_e32 v9, 0xffff0000, v2
	v_lshlrev_b32_e32 v10, 16, v3
	v_and_b32_e32 v11, 0xffff0000, v3
	v_mov_b64_e32 v[0:1], v[120:121]
	v_mov_b64_e32 v[2:3], v[122:123]
	s_mov_b32 s6, 0xbfb8aa3b
	s_mov_b32 s7, 0x3f317217
	v_add_f32_e32 v4, v0, v4
	v_add_f32_e32 v16, v0, v8
	v_min_f32_e32 v0, 0, v4
	v_mul_f32_e64 v4, |v4|, s6
	v_exp_f32_e32 v4, v4
	v_add_f32_e32 v5, v1, v5
	v_add_f32_e32 v18, v1, v9
	v_mul_f32_e64 v1, |v5|, s6
	v_add_f32_e32 v4, 1.0, v4
	v_cmp_gt_f32_e32 vcc, s2, v4
	v_exp_f32_e32 v1, v1
	v_min_f32_e32 v9, 0, v5
	v_cndmask_b32_e64 v8, 0, 32, vcc
	v_ldexp_f32 v4, v4, v8
	v_log_f32_e32 v4, v4
	v_add_f32_e32 v1, 1.0, v1
	v_add_f32_e32 v6, v2, v6
	v_add_f32_e32 v7, v3, v7
	v_mul_f32_e32 v8, 0x3f317217, v4
	v_fma_f32 v8, v4, s7, -v8
	v_fmac_f32_e32 v8, 0x3377d1cf, v4
	v_fmac_f32_e32 v8, 0x3f317217, v4
	v_cmp_lt_f32_e64 s[54:55], |v4|, s16
	s_nop 1
	v_cndmask_b32_e64 v4, v4, v8, s[54:55]
	v_cndmask_b32_e32 v8, 0, v20, vcc
	v_sub_f32_e32 v4, v4, v8
	v_min_f32_e32 v8, 0, v16
	v_mul_f32_e64 v16, |v16|, s6
	v_exp_f32_e32 v16, v16
	s_nop 0
	v_add_f32_e32 v16, 1.0, v16
	v_cmp_gt_f32_e32 vcc, s2, v16
	s_nop 1
	v_cndmask_b32_e64 v17, 0, 32, vcc
	v_ldexp_f32 v16, v16, v17
	v_log_f32_e32 v16, v16
	s_nop 0
	v_mul_f32_e32 v17, 0x3f317217, v16
	v_fma_f32 v17, v16, s7, -v17
	v_fmac_f32_e32 v17, 0x3377d1cf, v16
	v_fmac_f32_e32 v17, 0x3f317217, v16
	v_cmp_lt_f32_e64 s[54:55], |v16|, s16
	s_nop 1
	v_cndmask_b32_e64 v16, v16, v17, s[54:55]
	v_cndmask_b32_e32 v17, 0, v20, vcc
	v_cmp_gt_f32_e32 vcc, s2, v1
	v_sub_f32_e32 v16, v16, v17
	s_nop 0
	v_cndmask_b32_e64 v5, 0, 32, vcc
	v_ldexp_f32 v1, v1, v5
	v_log_f32_e32 v1, v1
	s_nop 0
	v_mul_f32_e32 v5, 0x3f317217, v1
	v_fma_f32 v5, v1, s7, -v5
	v_fmac_f32_e32 v5, 0x3377d1cf, v1
	v_fmac_f32_e32 v5, 0x3f317217, v1
	v_cmp_lt_f32_e64 s[54:55], |v1|, s16
	s_nop 1
	v_cndmask_b32_e64 v1, v1, v5, s[54:55]
	v_cndmask_b32_e32 v5, 0, v20, vcc
	v_sub_f32_e32 v17, v1, v5
	v_mul_f32_e64 v5, |v18|, s6
	v_exp_f32_e32 v5, v5
	v_min_f32_e32 v1, 0, v18
	v_pk_add_f32 v[8:9], v[8:9], v[16:17] neg_lo:[0,1] neg_hi:[0,1]
	v_add_f32_e32 v5, 1.0, v5
	v_cmp_gt_f32_e32 vcc, s2, v5
	s_nop 1
	v_cndmask_b32_e64 v18, 0, 32, vcc
	v_ldexp_f32 v5, v5, v18
	v_log_f32_e32 v5, v5
	s_nop 0
	v_mul_f32_e32 v18, 0x3f317217, v5
	v_fma_f32 v18, v5, s7, -v18
	v_fmac_f32_e32 v18, 0x3377d1cf, v5
	v_fmac_f32_e32 v18, 0x3f317217, v5
	v_cmp_lt_f32_e64 s[54:55], |v5|, s16
	s_nop 1
	v_cndmask_b32_e64 v5, v5, v18, s[54:55]
	v_cndmask_b32_e32 v18, 0, v20, vcc
	v_sub_f32_e32 v5, v5, v18
	v_pk_add_f32 v[4:5], v[0:1], v[4:5] neg_lo:[0,1] neg_hi:[0,1]
	s_nop 0
	v_pk_add_f32 v[16:17], v[8:9], v[4:5]
	ds_bpermute_b32 v0, v232, v16
	ds_bpermute_b32 v1, v232, v17
	s_waitcnt lgkmcnt(0)
	v_pk_add_f32 v[0:1], v[16:17], v[0:1]
	s_nop 0
	v_cndmask_b32_e64 v1, v1, v17, s[42:43]
	v_cndmask_b32_e64 v0, v0, v16, s[42:43]
	ds_bpermute_b32 v18, v233, v0
	ds_bpermute_b32 v19, v233, v1
	s_waitcnt lgkmcnt(0)
	v_pk_add_f32 v[18:19], v[0:1], v[18:19]
	s_nop 0
	v_cndmask_b32_e64 v1, v19, v1, s[44:45]
	v_cndmask_b32_e64 v0, v18, v0, s[44:45]
	ds_bpermute_b32 v18, v227, v0
	ds_bpermute_b32 v19, v227, v1
	s_waitcnt lgkmcnt(0)
	v_pk_add_f32 v[18:19], v[0:1], v[18:19]
	s_nop 0
	v_cndmask_b32_e64 v1, v19, v1, s[38:39]
	v_cndmask_b32_e64 v0, v18, v0, s[38:39]
	ds_bpermute_b32 v18, v228, v0
	ds_bpermute_b32 v19, v228, v1
	s_waitcnt lgkmcnt(0)
	v_pk_add_f32 v[18:19], v[0:1], v[18:19]
	s_nop 0
	v_cndmask_b32_e64 v1, v19, v1, s[46:47]
	v_cndmask_b32_e64 v0, v18, v0, s[46:47]
	ds_bpermute_b32 v18, v174, v0
	ds_bpermute_b32 v19, v174, v1
	s_waitcnt lgkmcnt(0)
	v_pk_add_f32 v[18:19], v[0:1], v[18:19]
	s_nop 0
	v_cndmask_b32_e64 v19, v19, v1, s[48:49]
	v_cndmask_b32_e64 v18, v18, v0, s[48:49]
	ds_bpermute_b32 v0, v170, v18
	ds_bpermute_b32 v1, v170, v19
	s_waitcnt lgkmcnt(0)
; DI void prep_unit(AP a, int l, int unit, LAS unsigned char* lds, int tid, int lane, int wave) {
;     ...
;         for (int h = 0; h < 4; ++h) {
;             const float xa = za[h] + fb[h], xb = zb[h] + fb[h];
;             const float la = fminf(xa, 0.f) - __logf(1.0f + __expf(-fabsf(xa))), lb = fminf(xb, 0.f) - __logf(1.0f + __expf(-fabsf(xb)));
;             const float tot = la + lb; float sc = tot;
; #pragma unroll
;             for (int o = 1; o < 64; o <<= 1) { const float v = __shfl_up(sc, o); if (lane >= o) sc += v; }
;             const float ex = sc - tot;
;             o0[h] = ex + la; o1[h] = ex + tot; tt[h] = sc;
;         }
;         *(v4f*)(floc + (size_t)r0 * 4) = o0; *(v4f*)(floc + (size_t)(r0 + 1) * 4) = o1;
;         if (lane == 63) *(v4f*)(ftot + (size_t)unit * 4) = tt;
	v_pk_add_f32 v[0:1], v[18:19], v[0:1]
	s_nop 0
	v_cndmask_b32_e64 v5, v0, v18, s[50:51]
	v_sub_f32_e32 v5, v5, v16
	v_add_f32_e32 v8, v4, v5
	v_add_f32_e32 v4, v16, v5
	v_add_f32_e32 v16, v2, v10
	v_min_f32_e32 v2, 0, v6
	v_mul_f32_e64 v6, |v6|, s6
	v_exp_f32_e32 v6, v6
	v_cndmask_b32_e64 v5, v1, v19, s[50:51]
	v_sub_f32_e32 v5, v5, v17
	v_add_f32_e32 v9, v9, v5
	v_add_f32_e32 v6, 1.0, v6
	v_cmp_gt_f32_e32 vcc, s2, v6
	v_add_f32_e32 v5, v17, v5
	v_add_f32_e32 v18, v3, v11
	v_cndmask_b32_e64 v10, 0, 32, vcc
	v_ldexp_f32 v6, v6, v10
	v_log_f32_e32 v6, v6
	v_mul_f32_e64 v3, |v7|, s6
	v_exp_f32_e32 v3, v3
	v_min_f32_e32 v11, 0, v7
	v_mul_f32_e32 v10, 0x3f317217, v6
	v_fma_f32 v10, v6, s7, -v10
	v_fmac_f32_e32 v10, 0x3377d1cf, v6
	v_fmac_f32_e32 v10, 0x3f317217, v6
	v_cmp_lt_f32_e64 s[54:55], |v6|, s16
	v_add_f32_e32 v3, 1.0, v3
	s_nop 0
	v_cndmask_b32_e64 v6, v6, v10, s[54:55]
	v_cndmask_b32_e32 v10, 0, v20, vcc
	v_sub_f32_e32 v6, v6, v10
	v_min_f32_e32 v10, 0, v16
	v_mul_f32_e64 v16, |v16|, s6
	v_exp_f32_e32 v16, v16
	s_nop 0
	v_add_f32_e32 v16, 1.0, v16
	v_cmp_gt_f32_e32 vcc, s2, v16
	s_nop 1
	v_cndmask_b32_e64 v17, 0, 32, vcc
	v_ldexp_f32 v16, v16, v17
	v_log_f32_e32 v16, v16
	s_nop 0
	v_mul_f32_e32 v17, 0x3f317217, v16
	v_fma_f32 v17, v16, s7, -v17
	v_fmac_f32_e32 v17, 0x3377d1cf, v16
	v_fmac_f32_e32 v17, 0x3f317217, v16
	v_cmp_lt_f32_e64 s[54:55], |v16|, s16
	s_nop 1
	v_cndmask_b32_e64 v16, v16, v17, s[54:55]
	v_cndmask_b32_e32 v17, 0, v20, vcc
	v_cmp_gt_f32_e32 vcc, s2, v3
	v_sub_f32_e32 v16, v16, v17
	s_nop 0
	v_cndmask_b32_e64 v7, 0, 32, vcc
	v_ldexp_f32 v3, v3, v7
	v_log_f32_e32 v3, v3
	s_nop 0
	v_mul_f32_e32 v7, 0x3f317217, v3
	v_fma_f32 v7, v3, s7, -v7
	v_fmac_f32_e32 v7, 0x3377d1cf, v3
	v_fmac_f32_e32 v7, 0x3f317217, v3
	v_cmp_lt_f32_e64 s[54:55], |v3|, s16
	s_nop 1
	v_cndmask_b32_e64 v3, v3, v7, s[54:55]
	v_cndmask_b32_e32 v7, 0, v20, vcc
	v_sub_f32_e32 v17, v3, v7
	v_mul_f32_e64 v7, |v18|, s6
	v_exp_f32_e32 v7, v7
	v_min_f32_e32 v3, 0, v18
	v_pk_add_f32 v[10:11], v[10:11], v[16:17] neg_lo:[0,1] neg_hi:[0,1]
	v_add_f32_e32 v7, 1.0, v7
	v_cmp_gt_f32_e32 vcc, s2, v7
	s_nop 1
	v_cndmask_b32_e64 v18, 0, 32, vcc
	v_ldexp_f32 v7, v7, v18
	v_log_f32_e32 v7, v7
	s_nop 0
	v_mul_f32_e32 v18, 0x3f317217, v7
	v_fma_f32 v18, v7, s7, -v18
	v_fmac_f32_e32 v18, 0x3377d1cf, v7
	v_fmac_f32_e32 v18, 0x3f317217, v7
	v_cmp_lt_f32_e64 s[54:55], |v7|, s16
	s_nop 1
	v_cndmask_b32_e64 v7, v7, v18, s[54:55]
	v_cndmask_b32_e32 v18, 0, v20, vcc
	v_sub_f32_e32 v7, v7, v18
	v_pk_add_f32 v[6:7], v[2:3], v[6:7] neg_lo:[0,1] neg_hi:[0,1]
	s_nop 0
	v_pk_add_f32 v[16:17], v[10:11], v[6:7]
	ds_bpermute_b32 v2, v232, v16
	ds_bpermute_b32 v3, v232, v17
	s_waitcnt lgkmcnt(0)
	v_pk_add_f32 v[2:3], v[16:17], v[2:3]
	s_nop 0
	v_cndmask_b32_e64 v3, v3, v17, s[42:43]
	v_cndmask_b32_e64 v2, v2, v16, s[42:43]
	ds_bpermute_b32 v18, v233, v2
	ds_bpermute_b32 v19, v233, v3
	s_waitcnt lgkmcnt(0)
	v_pk_add_f32 v[18:19], v[2:3], v[18:19]
	s_nop 0
	v_cndmask_b32_e64 v3, v19, v3, s[44:45]
	v_cndmask_b32_e64 v2, v18, v2, s[44:45]
	ds_bpermute_b32 v18, v227, v2
	ds_bpermute_b32 v19, v227, v3
	s_waitcnt lgkmcnt(0)
	v_pk_add_f32 v[18:19], v[2:3], v[18:19]
	s_nop 0
	v_cndmask_b32_e64 v3, v19, v3, s[38:39]
	v_cndmask_b32_e64 v2, v18, v2, s[38:39]
	ds_bpermute_b32 v18, v228, v2
	ds_bpermute_b32 v19, v228, v3
	s_waitcnt lgkmcnt(0)
	v_pk_add_f32 v[18:19], v[2:3], v[18:19]
	s_nop 0
	v_cndmask_b32_e64 v3, v19, v3, s[46:47]
	v_cndmask_b32_e64 v2, v18, v2, s[46:47]
	ds_bpermute_b32 v18, v174, v2
	ds_bpermute_b32 v19, v174, v3
	s_waitcnt lgkmcnt(0)
	v_pk_add_f32 v[18:19], v[2:3], v[18:19]
	s_nop 0
	v_cndmask_b32_e64 v19, v19, v3, s[48:49]
	v_cndmask_b32_e64 v18, v18, v2, s[48:49]
	ds_bpermute_b32 v2, v170, v18
	ds_bpermute_b32 v3, v170, v19
	s_waitcnt lgkmcnt(0)
	v_pk_add_f32 v[2:3], v[18:19], v[2:3]
	s_nop 0
	v_cndmask_b32_e64 v7, v2, v18, s[50:51]
	v_sub_f32_e32 v7, v7, v16
	v_add_f32_e32 v10, v6, v7
	v_add_f32_e32 v6, v16, v7
	v_cndmask_b32_e64 v7, v3, v19, s[50:51]
	v_sub_f32_e32 v7, v7, v17
	v_add_f32_e32 v11, v11, v7
	v_add_f32_e32 v7, v17, v7
	global_store_dwordx4 v[12:13], v[8:11], off
	s_nop 1
	v_lshl_add_u64 v[8:9], v[14:15], 4, s[12:13]
	global_store_dwordx4 v[8:9], v[4:7], off
	s_and_saveexec_b64 s[16:17], s[52:53]
	s_cbranch_execz .LBB0_649
	s_lshl_b64 s[6:7], s[14:15], 4
	s_add_u32 s6, s5, s6
	s_addc_u32 s7, s8, s7
	global_store_dwordx4 v65, v[0:3], s[6:7]
	s_branch .LBB0_649
